# residual-stream tile stores in the EpiResid epilogues marked nt (on top of saddr + no setprio + peeled iteration)
# baseline (speedup 1.0000x reference)
; #define PG8_STAGE(bufoff, gbase, voff) do { _Pragma("unroll") for (int _i = 0; _i < 2; ++_i) \
;         __builtin_amdgcn_global_load_lds((const unsigned*)((const char*)(gbase) + (voff)[_i]), (LAS unsigned*)(lds + (bufoff) + ldsw + _i * 8192), 16, 0, 0); } while (0)
; #define PG8_LDA(dst, b, h) do { _Pragma("unroll") for (int m = 0; m < 4; ++m) _Pragma("unroll") for (int k = 0; k < 2; ++k) dst[m][k] = *(const LAS bf16x8*)(lds + PG8_SA(b, h) + aoff + m * 2048 + k * 1024); } while (0)
; #define PG8_LDB(dst, b, h) do { _Pragma("unroll") for (int n = 0; n < 2; ++n) _Pragma("unroll") for (int k = 0; k < 2; ++k) dst[n][k] = *(const LAS bf16x8*)(lds + PG8_SB(b, h) + boff + n * 2048 + k * 1024); } while (0)
; #define PG8_MMA(ai, bj, At, Bt) do { __builtin_amdgcn_s_setprio(1); _Pragma("unroll") for (int m = 0; m < 4; ++m) _Pragma("unroll") for (int n = 0; n < 2; ++n) _Pragma("unroll") for (int k = 0; k < 2; ++k) \
;         acc[ai][bj][m][n] = __builtin_amdgcn_mfma_f32_16x16x32_bf16(Bt[n][k], At[m][k], acc[ai][bj][m][n], 0, 0, 0); __builtin_amdgcn_s_setprio(0); } while (0)
; #define PG8_WAIT_V(n) asm volatile("s_waitcnt vmcnt(" #n ")" ::: "memory")
; #define PG8_BAR __builtin_amdgcn_s_barrier()
; template <class Epi, class Sched, int KC, bool ALIGN_EPI = false, bool SP2 = false, bool ATILED = false>
; __device__ __forceinline__ void gemm_phase(LAS unsigned char* lds, const Gemm g, const Sched& S, const Epi& E, int wave_s) {
;     ...
;         for (int t = 0; t < nt; t += 2) {
;             const bool last = (t == nt - 2);
;             const char* a1 = cA + PG8_AOFF(t + 1);
;             const char* a2 = last ? nA : cA + PG8_AOFF(t + 2); const char* b2 = last ? nB : cB + (size_t)(t + 2) * kstep;
;             const char* a3 = a2 + kstep; const char* b3 = b2 + kstep;
;             if (last && has_next) S.a_ready(nxt);
;             if constexpr (SP2) {
;             PG8_LDB(B0, 0, 0); PG8_LDB(B1, 0, 1); PG8_SCHED; PG8_LDA(At, 0, 0); PG8_STAGE(PG8_SA(1, 1), a1 + hstepA, voffA);
;             PG8_WAIT_V(8); PG8_WAIT_L(0); PG8_BAR; PG8_MMA(0, 0, At, B0); PG8_MMA(0, 1, At, B1); PG8_BAR; PG8_SCHED;
;             PG8_LDA(At, 0, 1); PG8_STAGE(PG8_SB(0, 0), b2, voffB); PG8_STAGE(PG8_SB(0, 1), b2 + hstepB, voffB); PG8_STAGE(PG8_SA(0, 0), a2, voffA);
;             PG8_WAIT_V(8); PG8_WAIT_L(0); PG8_BAR; PG8_MMA(1, 0, At, B0); PG8_MMA(1, 1, At, B1); PG8_BAR; PG8_SCHED;
.LBB0_318:
	s_add_u32 s8, s20, 0x100
	s_addc_u32 s9, s21, 0
	s_add_i32 s53, 0, 0x10000
	s_cmpk_eq_i32 s52, 0x54
	s_cselect_b32 s25, s17, s9
	s_cselect_b32 s24, s16, s8
	s_cselect_b32 s23, s11, s51
	s_cselect_b32 s22, s10, s50
	s_add_i32 s54, 0, 0x14000
	v_add_u32_e32 v114, s53, v249
	v_add_u32_e32 v150, s54, v249
	ds_read_b128 v[82:85], v114
	ds_read_b128 v[94:97], v114 offset:1024
	ds_read_b128 v[106:109], v114 offset:2048
	ds_read_b128 v[114:117], v114 offset:3072
	ds_read_b128 v[130:133], v150
	ds_read_b128 v[134:137], v150 offset:1024
	ds_read_b128 v[146:149], v150 offset:2048
	ds_read_b128 v[150:153], v150 offset:3072
	s_add_i32 m0, s36, 0xc000
	ds_read_b128 v[154:157], v251
	ds_read_b128 v[166:169], v251 offset:1024
	ds_read_b128 v[170:173], v251 offset:2048
	ds_read_b128 v[174:177], v251 offset:3072
	ds_read_b128 v[178:181], v251 offset:4096
	ds_read_b128 v[182:185], v251 offset:5120
	ds_read_b128 v[186:189], v251 offset:6144
	ds_read_b128 v[194:197], v251 offset:7168
	global_load_lds_dwordx4 v204, s[20:21]
	s_add_i32 m0, s36, 0xe000
	s_nop 0
	global_load_lds_dwordx4 v202, s[20:21]
	s_waitcnt vmcnt(8)
	s_waitcnt lgkmcnt(0)
	s_barrier
	s_waitcnt lgkmcnt(0)
	v_mfma_f32_16x16x32_bf16 v[162:165], v[82:85], v[154:157], v[162:165]
	v_mfma_f32_16x16x32_bf16 v[158:161], v[106:109], v[154:157], v[158:161]
	v_mfma_f32_16x16x32_bf16 v[126:129], v[82:85], v[170:173], v[126:129]
	v_mfma_f32_16x16x32_bf16 v[122:125], v[106:109], v[170:173], v[122:125]
	v_mfma_f32_16x16x32_bf16 v[102:105], v[82:85], v[178:181], v[102:105]
	v_mfma_f32_16x16x32_bf16 v[98:101], v[106:109], v[178:181], v[98:101]
	v_mfma_f32_16x16x32_bf16 v[78:81], v[82:85], v[186:189], v[78:81]
	v_mfma_f32_16x16x32_bf16 v[74:77], v[106:109], v[186:189], v[74:77]
	v_mfma_f32_16x16x32_bf16 v[162:165], v[94:97], v[166:169], v[162:165]
	v_mfma_f32_16x16x32_bf16 v[158:161], v[114:117], v[166:169], v[158:161]
	v_mfma_f32_16x16x32_bf16 v[126:129], v[94:97], v[174:177], v[126:129]
	v_mfma_f32_16x16x32_bf16 v[122:125], v[114:117], v[174:177], v[122:125]
	v_mfma_f32_16x16x32_bf16 v[102:105], v[94:97], v[182:185], v[102:105]
	v_mfma_f32_16x16x32_bf16 v[98:101], v[114:117], v[182:185], v[98:101]
	v_mfma_f32_16x16x32_bf16 v[78:81], v[94:97], v[194:197], v[78:81]
	v_mfma_f32_16x16x32_bf16 v[74:77], v[114:117], v[194:197], v[74:77]
	v_mfma_f32_16x16x32_bf16 v[142:145], v[130:133], v[154:157], v[142:145]
	v_mfma_f32_16x16x32_bf16 v[138:141], v[146:149], v[154:157], v[138:141]
	v_mfma_f32_16x16x32_bf16 v[118:121], v[130:133], v[170:173], v[118:121]
	v_mfma_f32_16x16x32_bf16 v[110:113], v[146:149], v[170:173], v[110:113]
	v_mfma_f32_16x16x32_bf16 v[90:93], v[130:133], v[178:181], v[90:93]
	v_mfma_f32_16x16x32_bf16 v[86:89], v[146:149], v[178:181], v[86:89]
	v_mfma_f32_16x16x32_bf16 v[70:73], v[130:133], v[186:189], v[70:73]
	v_mfma_f32_16x16x32_bf16 v[66:69], v[146:149], v[186:189], v[66:69]
	v_mfma_f32_16x16x32_bf16 v[142:145], v[134:137], v[166:169], v[142:145]
	v_mfma_f32_16x16x32_bf16 v[138:141], v[150:153], v[166:169], v[138:141]
	v_mfma_f32_16x16x32_bf16 v[118:121], v[134:137], v[174:177], v[118:121]
	v_mfma_f32_16x16x32_bf16 v[110:113], v[150:153], v[174:177], v[110:113]
	v_mfma_f32_16x16x32_bf16 v[90:93], v[134:137], v[182:185], v[90:93]
	v_mfma_f32_16x16x32_bf16 v[86:89], v[150:153], v[182:185], v[86:89]
	v_mfma_f32_16x16x32_bf16 v[70:73], v[134:137], v[194:197], v[70:73]
	v_mfma_f32_16x16x32_bf16 v[66:69], v[150:153], v[194:197], v[66:69]
	s_barrier
	s_add_i32 s20, s53, s35
	s_mov_b32 m0, s20
	ds_read_b128 v[154:157], v251 offset:16384
	ds_read_b128 v[166:169], v251 offset:17408
	ds_read_b128 v[170:173], v251 offset:18432
	ds_read_b128 v[174:177], v251 offset:19456
	ds_read_b128 v[178:181], v251 offset:20480
	ds_read_b128 v[182:185], v251 offset:21504
	ds_read_b128 v[186:189], v251 offset:22528
	ds_read_b128 v[194:197], v251 offset:23552
	global_load_lds_dwordx4 v0, s[22:23]
	s_add_i32 m0, s20, 0x2000
	s_add_u32 s20, s22, 0x58000
	s_addc_u32 s21, s23, 0
	s_add_i32 s53, s54, s35
	global_load_lds_dwordx4 v198, s[22:23]
	s_mov_b32 m0, s53
	s_nop 0
	global_load_lds_dwordx4 v0, s[20:21]
	s_add_i32 m0, s53, 0x2000
	s_nop 0
	global_load_lds_dwordx4 v198, s[20:21]
	s_mov_b32 m0, s36
	s_nop 0
	global_load_lds_dwordx4 v190, s[24:25]
	s_mov_b32 m0, s37
	s_nop 0
	global_load_lds_dwordx4 v192, s[24:25]
	s_waitcnt vmcnt(8)
	s_waitcnt lgkmcnt(0)
	s_barrier
	s_waitcnt lgkmcnt(0)
	v_mfma_f32_16x16x32_bf16 v[62:65], v[82:85], v[154:157], v[62:65]
	v_mfma_f32_16x16x32_bf16 v[58:61], v[106:109], v[154:157], v[58:61]
	v_mfma_f32_16x16x32_bf16 v[46:49], v[82:85], v[170:173], v[46:49]
	v_mfma_f32_16x16x32_bf16 v[42:45], v[106:109], v[170:173], v[42:45]
	v_mfma_f32_16x16x32_bf16 v[30:33], v[82:85], v[178:181], v[30:33]
	v_mfma_f32_16x16x32_bf16 v[26:29], v[106:109], v[178:181], v[26:29]
	v_mfma_f32_16x16x32_bf16 v[14:17], v[82:85], v[186:189], v[14:17]
	v_mfma_f32_16x16x32_bf16 v[10:13], v[106:109], v[186:189], v[10:13]
	v_mfma_f32_16x16x32_bf16 v[62:65], v[94:97], v[166:169], v[62:65]
	v_mfma_f32_16x16x32_bf16 v[58:61], v[114:117], v[166:169], v[58:61]
	v_mfma_f32_16x16x32_bf16 v[46:49], v[94:97], v[174:177], v[46:49]
	v_mfma_f32_16x16x32_bf16 v[42:45], v[114:117], v[174:177], v[42:45]
	v_mfma_f32_16x16x32_bf16 v[30:33], v[94:97], v[182:185], v[30:33]
	v_mfma_f32_16x16x32_bf16 v[26:29], v[114:117], v[182:185], v[26:29]
	v_mfma_f32_16x16x32_bf16 v[14:17], v[94:97], v[194:197], v[14:17]
	v_mfma_f32_16x16x32_bf16 v[10:13], v[114:117], v[194:197], v[10:13]
	v_mfma_f32_16x16x32_bf16 v[54:57], v[130:133], v[154:157], v[54:57]
	v_mfma_f32_16x16x32_bf16 v[50:53], v[146:149], v[154:157], v[50:53]
	v_mfma_f32_16x16x32_bf16 v[38:41], v[130:133], v[170:173], v[38:41]
	v_mfma_f32_16x16x32_bf16 v[34:37], v[146:149], v[170:173], v[34:37]
	v_mfma_f32_16x16x32_bf16 v[22:25], v[130:133], v[178:181], v[22:25]
	v_mfma_f32_16x16x32_bf16 v[18:21], v[146:149], v[178:181], v[18:21]
	v_mfma_f32_16x16x32_bf16 v[6:9], v[130:133], v[186:189], v[6:9]
	v_mfma_f32_16x16x32_bf16 v[2:5], v[146:149], v[186:189], v[2:5]
	v_mfma_f32_16x16x32_bf16 v[54:57], v[134:137], v[166:169], v[54:57]
	v_mfma_f32_16x16x32_bf16 v[50:53], v[150:153], v[166:169], v[50:53]
	v_mfma_f32_16x16x32_bf16 v[38:41], v[134:137], v[174:177], v[38:41]
	v_mfma_f32_16x16x32_bf16 v[34:37], v[150:153], v[174:177], v[34:37]
	v_mfma_f32_16x16x32_bf16 v[22:25], v[134:137], v[182:185], v[22:25]
	v_mfma_f32_16x16x32_bf16 v[18:21], v[150:153], v[182:185], v[18:21]
	v_mfma_f32_16x16x32_bf16 v[6:9], v[134:137], v[194:197], v[6:9]
	v_mfma_f32_16x16x32_bf16 v[2:5], v[150:153], v[194:197], v[2:5]
	s_barrier
; #define PG8_STAGE(bufoff, gbase, voff) do { _Pragma("unroll") for (int _i = 0; _i < 2; ++_i) \
;         __builtin_amdgcn_global_load_lds((const unsigned*)((const char*)(gbase) + (voff)[_i]), (LAS unsigned*)(lds + (bufoff) + ldsw + _i * 8192), 16, 0, 0); } while (0)
; #define PG8_LDA(dst, b, h) do { _Pragma("unroll") for (int m = 0; m < 4; ++m) _Pragma("unroll") for (int k = 0; k < 2; ++k) dst[m][k] = *(const LAS bf16x8*)(lds + PG8_SA(b, h) + aoff + m * 2048 + k * 1024); } while (0)
; #define PG8_LDB(dst, b, h) do { _Pragma("unroll") for (int n = 0; n < 2; ++n) _Pragma("unroll") for (int k = 0; k < 2; ++k) dst[n][k] = *(const LAS bf16x8*)(lds + PG8_SB(b, h) + boff + n * 2048 + k * 1024); } while (0)
; #define PG8_MMA(ai, bj, At, Bt) do { __builtin_amdgcn_s_setprio(1); _Pragma("unroll") for (int m = 0; m < 4; ++m) _Pragma("unroll") for (int n = 0; n < 2; ++n) _Pragma("unroll") for (int k = 0; k < 2; ++k) \
;         acc[ai][bj][m][n] = __builtin_amdgcn_mfma_f32_16x16x32_bf16(Bt[n][k], At[m][k], acc[ai][bj][m][n], 0, 0, 0); __builtin_amdgcn_s_setprio(0); } while (0)
; #define PG8_WAIT_V(n) asm volatile("s_waitcnt vmcnt(" #n ")" ::: "memory")
; #define PG8_WAIT_L(n) asm volatile("s_waitcnt lgkmcnt(" #n ")" ::: "memory")
; #define PG8_BAR __builtin_amdgcn_s_barrier()
; #define PG8_SCHED __builtin_amdgcn_sched_barrier(0)
; template <class Epi, class Sched, int KC, bool ALIGN_EPI = false, bool SP2 = false, bool ATILED = false>
; __device__ __forceinline__ void gemm_phase(LAS unsigned char* lds, const Gemm g, const Sched& S, const Epi& E, int wave_s) {
;     ...
;             PG8_LDB(B0, 1, 0); PG8_LDB(B1, 1, 1); PG8_SCHED; PG8_LDA(At, 1, 0); PG8_STAGE(PG8_SA(0, 1), a2 + hstepA, voffA);
;             PG8_WAIT_V(8); PG8_WAIT_L(0); PG8_BAR; PG8_MMA(0, 0, At, B0); PG8_MMA(0, 1, At, B1); PG8_BAR; PG8_SCHED;
;             PG8_LDA(At, 1, 1); PG8_STAGE(PG8_SB(1, 0), b3, voffB); PG8_STAGE(PG8_SB(1, 1), b3 + hstepB, voffB); PG8_STAGE(PG8_SA(1, 0), a3, voffA);
;             PG8_WAIT_V(8); PG8_WAIT_L(0); PG8_BAR; PG8_MMA(1, 0, At, B0); PG8_MMA(1, 1, At, B1); PG8_BAR; PG8_SCHED;
	s_add_i32 s53, 0, 0x18000
	s_add_i32 s54, 0, 0x1c000
	v_add_u32_e32 v114, s53, v249
	v_add_u32_e32 v150, s54, v249
	ds_read_b128 v[82:85], v114
	ds_read_b128 v[94:97], v114 offset:1024
	ds_read_b128 v[106:109], v114 offset:2048
	ds_read_b128 v[114:117], v114 offset:3072
	ds_read_b128 v[130:133], v150
	ds_read_b128 v[134:137], v150 offset:1024
	ds_read_b128 v[146:149], v150 offset:2048
	ds_read_b128 v[150:153], v150 offset:3072
	s_add_u32 s20, s24, 0x160000
	s_addc_u32 s21, s25, 0
	s_mov_b32 m0, s38
	ds_read_b128 v[154:157], v251 offset:32768
	ds_read_b128 v[166:169], v251 offset:33792
	ds_read_b128 v[170:173], v251 offset:34816
	ds_read_b128 v[174:177], v251 offset:35840
	ds_read_b128 v[178:181], v251 offset:36864
	ds_read_b128 v[182:185], v251 offset:37888
	ds_read_b128 v[186:189], v251 offset:38912
	ds_read_b128 v[194:197], v251 offset:39936
	global_load_lds_dwordx4 v190, s[20:21]
	s_mov_b32 m0, s39
	s_nop 0
	global_load_lds_dwordx4 v192, s[20:21]
	s_waitcnt vmcnt(8)
	s_waitcnt lgkmcnt(0)
	s_barrier
	s_waitcnt lgkmcnt(0)
	v_mfma_f32_16x16x32_bf16 v[162:165], v[82:85], v[154:157], v[162:165]
	v_mfma_f32_16x16x32_bf16 v[158:161], v[106:109], v[154:157], v[158:161]
	v_mfma_f32_16x16x32_bf16 v[126:129], v[82:85], v[170:173], v[126:129]
	v_mfma_f32_16x16x32_bf16 v[122:125], v[106:109], v[170:173], v[122:125]
	v_mfma_f32_16x16x32_bf16 v[102:105], v[82:85], v[178:181], v[102:105]
	v_mfma_f32_16x16x32_bf16 v[98:101], v[106:109], v[178:181], v[98:101]
	v_mfma_f32_16x16x32_bf16 v[78:81], v[82:85], v[186:189], v[78:81]
	v_mfma_f32_16x16x32_bf16 v[74:77], v[106:109], v[186:189], v[74:77]
	v_mfma_f32_16x16x32_bf16 v[162:165], v[94:97], v[166:169], v[162:165]
	v_mfma_f32_16x16x32_bf16 v[158:161], v[114:117], v[166:169], v[158:161]
	v_mfma_f32_16x16x32_bf16 v[126:129], v[94:97], v[174:177], v[126:129]
	v_mfma_f32_16x16x32_bf16 v[122:125], v[114:117], v[174:177], v[122:125]
	v_mfma_f32_16x16x32_bf16 v[102:105], v[94:97], v[182:185], v[102:105]
	v_mfma_f32_16x16x32_bf16 v[98:101], v[114:117], v[182:185], v[98:101]
	v_mfma_f32_16x16x32_bf16 v[78:81], v[94:97], v[194:197], v[78:81]
	v_mfma_f32_16x16x32_bf16 v[74:77], v[114:117], v[194:197], v[74:77]
	v_mfma_f32_16x16x32_bf16 v[142:145], v[130:133], v[154:157], v[142:145]
	v_mfma_f32_16x16x32_bf16 v[138:141], v[146:149], v[154:157], v[138:141]
	v_mfma_f32_16x16x32_bf16 v[118:121], v[130:133], v[170:173], v[118:121]
	v_mfma_f32_16x16x32_bf16 v[110:113], v[146:149], v[170:173], v[110:113]
	v_mfma_f32_16x16x32_bf16 v[90:93], v[130:133], v[178:181], v[90:93]
	v_mfma_f32_16x16x32_bf16 v[86:89], v[146:149], v[178:181], v[86:89]
	v_mfma_f32_16x16x32_bf16 v[70:73], v[130:133], v[186:189], v[70:73]
	v_mfma_f32_16x16x32_bf16 v[66:69], v[146:149], v[186:189], v[66:69]
	v_mfma_f32_16x16x32_bf16 v[142:145], v[134:137], v[166:169], v[142:145]
	v_mfma_f32_16x16x32_bf16 v[138:141], v[150:153], v[166:169], v[138:141]
	v_mfma_f32_16x16x32_bf16 v[118:121], v[134:137], v[174:177], v[118:121]
	v_mfma_f32_16x16x32_bf16 v[110:113], v[150:153], v[174:177], v[110:113]
	v_mfma_f32_16x16x32_bf16 v[90:93], v[134:137], v[182:185], v[90:93]
	v_mfma_f32_16x16x32_bf16 v[86:89], v[150:153], v[182:185], v[86:89]
	v_mfma_f32_16x16x32_bf16 v[70:73], v[134:137], v[194:197], v[70:73]
	v_mfma_f32_16x16x32_bf16 v[66:69], v[150:153], v[194:197], v[66:69]
	s_barrier
	s_add_u32 s98, s22, 0x80
	s_addc_u32 s99, s23, 0
	s_add_u32 s100, s24, 0x80
	s_addc_u32 s101, s25, 0
	s_add_i32 s20, s53, s35
	s_mov_b32 m0, s20
	ds_read_b128 v[154:157], v251 offset:49152
	ds_read_b128 v[166:169], v251 offset:50176
	ds_read_b128 v[170:173], v251 offset:51200
	ds_read_b128 v[174:177], v251 offset:52224
	ds_read_b128 v[178:181], v251 offset:53248
	ds_read_b128 v[182:185], v251 offset:54272
	ds_read_b128 v[186:189], v251 offset:55296
	ds_read_b128 v[194:197], v251 offset:56320
	global_load_lds_dwordx4 v0, s[98:99]
	s_add_i32 m0, s20, 0x2000
	s_add_u32 s20, s22, 0x58080
	s_addc_u32 s21, s23, 0
	s_add_i32 s22, s54, s35
	global_load_lds_dwordx4 v198, s[98:99]
	s_mov_b32 m0, s22
	s_nop 0
	global_load_lds_dwordx4 v0, s[20:21]
	s_add_i32 m0, s22, 0x2000
	s_nop 0
	global_load_lds_dwordx4 v198, s[20:21]
	s_mov_b32 m0, s43
	s_nop 0
	global_load_lds_dwordx4 v190, s[100:101]
	s_mov_b32 m0, s44
	s_nop 0
	global_load_lds_dwordx4 v192, s[100:101]
	s_waitcnt vmcnt(8)
	s_waitcnt lgkmcnt(0)
	s_barrier
	s_waitcnt lgkmcnt(0)
	v_mfma_f32_16x16x32_bf16 v[62:65], v[82:85], v[154:157], v[62:65]
	v_mfma_f32_16x16x32_bf16 v[58:61], v[106:109], v[154:157], v[58:61]
	v_mfma_f32_16x16x32_bf16 v[46:49], v[82:85], v[170:173], v[46:49]
	v_mfma_f32_16x16x32_bf16 v[42:45], v[106:109], v[170:173], v[42:45]
	v_mfma_f32_16x16x32_bf16 v[30:33], v[82:85], v[178:181], v[30:33]
	v_mfma_f32_16x16x32_bf16 v[26:29], v[106:109], v[178:181], v[26:29]
	v_mfma_f32_16x16x32_bf16 v[14:17], v[82:85], v[186:189], v[14:17]
	v_mfma_f32_16x16x32_bf16 v[10:13], v[106:109], v[186:189], v[10:13]
	v_mfma_f32_16x16x32_bf16 v[62:65], v[94:97], v[166:169], v[62:65]
	v_mfma_f32_16x16x32_bf16 v[58:61], v[114:117], v[166:169], v[58:61]
	v_mfma_f32_16x16x32_bf16 v[46:49], v[94:97], v[174:177], v[46:49]
	v_mfma_f32_16x16x32_bf16 v[42:45], v[114:117], v[174:177], v[42:45]
	v_mfma_f32_16x16x32_bf16 v[30:33], v[94:97], v[182:185], v[30:33]
	v_mfma_f32_16x16x32_bf16 v[26:29], v[114:117], v[182:185], v[26:29]
	v_mfma_f32_16x16x32_bf16 v[14:17], v[94:97], v[194:197], v[14:17]
	v_mfma_f32_16x16x32_bf16 v[10:13], v[114:117], v[194:197], v[10:13]
	v_mfma_f32_16x16x32_bf16 v[54:57], v[130:133], v[154:157], v[54:57]
	v_mfma_f32_16x16x32_bf16 v[50:53], v[146:149], v[154:157], v[50:53]
	v_mfma_f32_16x16x32_bf16 v[38:41], v[130:133], v[170:173], v[38:41]
	v_mfma_f32_16x16x32_bf16 v[34:37], v[146:149], v[170:173], v[34:37]
	v_mfma_f32_16x16x32_bf16 v[22:25], v[130:133], v[178:181], v[22:25]
	v_mfma_f32_16x16x32_bf16 v[18:21], v[146:149], v[178:181], v[18:21]
	v_mfma_f32_16x16x32_bf16 v[6:9], v[130:133], v[186:189], v[6:9]
	v_mfma_f32_16x16x32_bf16 v[2:5], v[146:149], v[186:189], v[2:5]
	v_mfma_f32_16x16x32_bf16 v[54:57], v[134:137], v[166:169], v[54:57]
	v_mfma_f32_16x16x32_bf16 v[50:53], v[150:153], v[166:169], v[50:53]
	v_mfma_f32_16x16x32_bf16 v[38:41], v[134:137], v[174:177], v[38:41]
	v_mfma_f32_16x16x32_bf16 v[34:37], v[150:153], v[174:177], v[34:37]
	v_mfma_f32_16x16x32_bf16 v[22:25], v[134:137], v[182:185], v[22:25]
	v_mfma_f32_16x16x32_bf16 v[18:21], v[150:153], v[182:185], v[18:21]
	v_mfma_f32_16x16x32_bf16 v[6:9], v[134:137], v[194:197], v[6:9]
	v_mfma_f32_16x16x32_bf16 v[2:5], v[150:153], v[194:197], v[2:5]
	s_barrier
; #define GAS __attribute__((address_space(1)))
; DI unsigned cvtpk(float lo, float hi) { unsigned r; asm volatile("v_cvt_pk_bf16_f32 %0, %1, %2" : "=v"(r) : "v"(lo), "v"(hi)); return r; }
;     DI void operator()(const f32x4 (&acc)[2][2][4][2], const Unit& u, int wr, int wc, int fr, int fq) const {
;         const int row0 = u.pm * BM + wr * 64 + fr, col0 = u.pn * BM + wc * 64 + 8 * fq;
;         const size_t hbase = (size_t)u.pn * ((size_t)M * 256) + wc * 64 + 8 * fq;
;         u32x4 H[2][4][2];
; #pragma unroll
;         for (int ai = 0; ai < 2; ++ai)
; #pragma unroll
;             for (int m = 0; m < 4; ++m)
; #pragma unroll
;                 for (int bj = 0; bj < 2; ++bj) H[ai][m][bj] = *(const GAS u32x4*)(hi + hbase + (size_t)(row0 + ai * HALF + m * 16) * 256 + bj * 32);
;         asm volatile("" ::: "memory");
; #pragma unroll
;         for (int ai = 0; ai < 2; ++ai) {
; #pragma unroll
;             for (int m = 0; m < 4; ++m) {
;                 const int r = row0 + ai * HALF + m * 16; const size_t off = (size_t)r * DM + col0; float ss = 0.f;
; #pragma unroll
;                 for (int bj = 0; bj < 2; ++bj) {
;                     const u32x4 h = H[ai][m][bj];
;                     const f32x4 a0 = acc[ai][bj][m][0], a1 = acc[ai][bj][m][1];
;                     float v[8];
;                     v[0] = bflo(h.x) + a0[0] * scale; v[1] = bfhi(h.x) + a0[1] * scale;
;                     v[2] = bflo(h.y) + a0[2] * scale; v[3] = bfhi(h.y) + a0[3] * scale;
;                     v[4] = bflo(h.z) + a1[0] * scale; v[5] = bfhi(h.z) + a1[1] * scale;
;                     v[6] = bflo(h.w) + a1[2] * scale; v[7] = bfhi(h.w) + a1[3] * scale;
; #pragma unroll
;                     for (int e = 0; e < 8; ++e) ss += v[e] * v[e];
;                     u32x4 nh;
;                     nh.x = cvtpk(v[0], v[1]); nh.y = cvtpk(v[2], v[3]); nh.z = cvtpk(v[4], v[5]); nh.w = cvtpk(v[6], v[7]);
;                     *(GAS u32x4*)(hi + hbase + (size_t)r * 256 + bj * 32) = nh;
;                     if (out) { *(GAS f32x4*)(out + off + bj * 32) = (f32x4){v[0], v[1], v[2], v[3]}; *(GAS f32x4*)(out + off + bj * 32 + 4) = (f32x4){v[4], v[5], v[6], v[7]}; }
	s_add_i32 s52, s52, 2
	s_add_u32 s50, s50, 0x100
	s_addc_u32 s51, s51, 0
	s_cmpk_gt_u32 s52, 0x55
	s_mov_b64 s[20:21], s[8:9]
	s_cbranch_scc0 .LBB0_318
	v_lshl_add_u32 v206, s19, 8, v248
	s_ashr_i32 s19, s18, 31
	s_lshl_b64 s[8:9], s[18:19], 23
	v_ashrrev_i32_e32 v207, 31, v206
	v_or_b32_e32 v236, 16, v206
	v_lshl_add_u64 v[82:83], v[200:201], 0, s[8:9]
	v_lshlrev_b64 v[84:85], 9, v[206:207]
	v_ashrrev_i32_e32 v237, 31, v236
	v_or_b32_e32 v232, 32, v206
	v_lshl_add_u64 v[238:239], v[82:83], 0, v[84:85]
	v_lshlrev_b64 v[84:85], 9, v[236:237]
	v_ashrrev_i32_e32 v233, 31, v232
	v_or_b32_e32 v228, 48, v206
	v_lshl_add_u64 v[234:235], v[82:83], 0, v[84:85]
	v_lshlrev_b64 v[84:85], 9, v[232:233]
	v_ashrrev_i32_e32 v229, 31, v228
	v_add_u32_e32 v224, 0x80, v206
	v_lshl_add_u64 v[230:231], v[82:83], 0, v[84:85]
	v_lshlrev_b64 v[84:85], 9, v[228:229]
	v_ashrrev_i32_e32 v225, 31, v224
	v_add_u32_e32 v220, 0x90, v206
	global_load_dwordx4 v[194:197], v[238:239], off
	global_load_dwordx4 v[186:189], v[238:239], off offset:64
	v_lshl_add_u64 v[226:227], v[82:83], 0, v[84:85]
	v_lshlrev_b64 v[84:85], 9, v[224:225]
	v_ashrrev_i32_e32 v221, 31, v220
	v_add_u32_e32 v216, 0xa0, v206
	v_lshl_add_u64 v[222:223], v[82:83], 0, v[84:85]
	v_lshlrev_b64 v[84:85], 9, v[220:221]
	v_ashrrev_i32_e32 v217, 31, v216
	v_add_u32_e32 v210, 0xb0, v206
	v_lshl_add_u64 v[218:219], v[82:83], 0, v[84:85]
	v_lshlrev_b64 v[84:85], 9, v[216:217]
	v_ashrrev_i32_e32 v211, 31, v210
	v_lshl_add_u64 v[214:215], v[82:83], 0, v[84:85]
	v_lshlrev_b64 v[84:85], 9, v[210:211]
	v_lshl_add_u64 v[208:209], v[82:83], 0, v[84:85]
	global_load_dwordx4 v[182:185], v[234:235], off
	global_load_dwordx4 v[178:181], v[234:235], off offset:64
	global_load_dwordx4 v[174:177], v[230:231], off
	global_load_dwordx4 v[170:173], v[230:231], off offset:64
	global_load_dwordx4 v[166:169], v[226:227], off
	global_load_dwordx4 v[154:157], v[226:227], off offset:64
	global_load_dwordx4 v[150:153], v[222:223], off
	global_load_dwordx4 v[146:149], v[222:223], off offset:64
	global_load_dwordx4 v[134:137], v[218:219], off
	global_load_dwordx4 v[130:133], v[218:219], off offset:64
	global_load_dwordx4 v[114:117], v[214:215], off
	global_load_dwordx4 v[106:109], v[214:215], off offset:64
	global_load_dwordx4 v[94:97], v[208:209], off
	global_load_dwordx4 v[82:85], v[208:209], off offset:64
	v_lshl_or_b32 v212, s18, 8, v250
	v_ashrrev_i32_e32 v213, 31, v212
	v_lshlrev_b64 v[240:241], 11, v[206:207]
	v_lshl_add_u64 v[240:241], v[240:241], 0, v[212:213]
	s_andn2_b64 vcc, exec, s[14:15]
	v_lshl_add_u64 v[240:241], v[240:241], 2, s[12:13]
	s_waitcnt vmcnt(0)
	v_lshlrev_b32_e32 v252, 16, v194
	v_and_b32_e32 v253, 0xffff0000, v194
	v_lshlrev_b32_e32 v194, 16, v195
	v_and_b32_e32 v195, 0xffff0000, v195
	v_pk_fma_f32 v[164:165], v[164:165], 0.5, v[194:195] op_sel_hi:[1,0,1]
	v_lshlrev_b32_e32 v194, 16, v196
	v_and_b32_e32 v195, 0xffff0000, v196
	v_pk_fma_f32 v[158:159], v[158:159], 0.5, v[194:195] op_sel_hi:[1,0,1]
	v_lshlrev_b32_e32 v194, 16, v197
	v_and_b32_e32 v195, 0xffff0000, v197
	v_pk_fma_f32 v[162:163], v[162:163], 0.5, v[252:253] op_sel_hi:[1,0,1]
	v_pk_fma_f32 v[160:161], v[160:161], 0.5, v[194:195] op_sel_hi:[1,0,1]
	v_cvt_pk_bf16_f32 v194, v162, v163
	v_cvt_pk_bf16_f32 v195, v164, v165
	v_cvt_pk_bf16_f32 v196, v158, v159
	s_nop 0
	v_cvt_pk_bf16_f32 v197, v160, v161
	global_store_dwordx4 v[238:239], v[194:197], off nt
	s_nop 1
	v_cndmask_b32_e64 v194, 0, 1, s[14:15]
	v_cmp_ne_u32_e64 s[8:9], 1, v194
	s_cbranch_vccnz .LBB0_321
	global_store_dwordx4 v[240:241], v[162:165], off
	global_store_dwordx4 v[240:241], v[158:161], off offset:16
.LBB0_321:
	v_lshlrev_b32_e32 v194, 16, v186
	v_and_b32_e32 v195, 0xffff0000, v186
	v_lshlrev_b32_e32 v186, 16, v187
	v_and_b32_e32 v187, 0xffff0000, v187
	v_pk_fma_f32 v[144:145], v[144:145], 0.5, v[186:187] op_sel_hi:[1,0,1]
	v_lshlrev_b32_e32 v186, 16, v188
	v_and_b32_e32 v187, 0xffff0000, v188
	v_pk_fma_f32 v[138:139], v[138:139], 0.5, v[186:187] op_sel_hi:[1,0,1]
	v_lshlrev_b32_e32 v186, 16, v189
	v_and_b32_e32 v187, 0xffff0000, v189
	v_pk_fma_f32 v[142:143], v[142:143], 0.5, v[194:195] op_sel_hi:[1,0,1]
	v_pk_fma_f32 v[140:141], v[140:141], 0.5, v[186:187] op_sel_hi:[1,0,1]
	s_and_b64 vcc, exec, s[8:9]
	v_cvt_pk_bf16_f32 v186, v142, v143
	v_cvt_pk_bf16_f32 v187, v144, v145
	v_cvt_pk_bf16_f32 v188, v138, v139
	v_cvt_pk_bf16_f32 v189, v140, v141
	global_store_dwordx4 v[238:239], v[186:189], off offset:64 nt
	s_cbranch_vccnz .LBB0_323
	global_store_dwordx4 v[240:241], v[142:145], off offset:128
	global_store_dwordx4 v[240:241], v[138:141], off offset:144

; #define GAS __attribute__((address_space(1)))
; DI unsigned cvtpk(float lo, float hi) { unsigned r; asm volatile("v_cvt_pk_bf16_f32 %0, %1, %2" : "=v"(r) : "v"(lo), "v"(hi)); return r; }
;     DI void operator()(const f32x4 (&acc)[2][2][4][2], const Unit& u, int wr, int wc, int fr, int fq) const {
;     ...
;             for (int m = 0; m < 4; ++m) {
;                 const int r = row0 + ai * HALF + m * 16; const size_t off = (size_t)r * DM + col0; float ss = 0.f;
; #pragma unroll
;                 for (int bj = 0; bj < 2; ++bj) {
;                     const u32x4 h = H[ai][m][bj];
;                     const f32x4 a0 = acc[ai][bj][m][0], a1 = acc[ai][bj][m][1];
;                     float v[8];
;                     v[0] = bflo(h.x) + a0[0] * scale; v[1] = bfhi(h.x) + a0[1] * scale;
;                     v[2] = bflo(h.y) + a0[2] * scale; v[3] = bfhi(h.y) + a0[3] * scale;
;                     v[4] = bflo(h.z) + a1[0] * scale; v[5] = bfhi(h.z) + a1[1] * scale;
;                     v[6] = bflo(h.w) + a1[2] * scale; v[7] = bfhi(h.w) + a1[3] * scale;
; #pragma unroll
;                     for (int e = 0; e < 8; ++e) ss += v[e] * v[e];
;                     u32x4 nh;
;                     nh.x = cvtpk(v[0], v[1]); nh.y = cvtpk(v[2], v[3]); nh.z = cvtpk(v[4], v[5]); nh.w = cvtpk(v[6], v[7]);
;                     *(GAS u32x4*)(hi + hbase + (size_t)r * 256 + bj * 32) = nh;
;                     if (out) { *(GAS f32x4*)(out + off + bj * 32) = (f32x4){v[0], v[1], v[2], v[3]}; *(GAS f32x4*)(out + off + bj * 32 + 4) = (f32x4){v[4], v[5], v[6], v[7]}; }
.LBB0_325:
	s_or_b64 exec, exec, s[20:21]
	v_lshlrev_b64 v[138:139], 11, v[236:237]
	v_lshl_add_u64 v[142:143], v[138:139], 0, v[212:213]
	v_lshlrev_b32_e32 v138, 16, v182
	v_and_b32_e32 v139, 0xffff0000, v182
	v_pk_fma_f32 v[126:127], v[126:127], 0.5, v[138:139] op_sel_hi:[1,0,1]
	v_lshlrev_b32_e32 v138, 16, v183
	v_and_b32_e32 v139, 0xffff0000, v183
	v_pk_fma_f32 v[128:129], v[128:129], 0.5, v[138:139] op_sel_hi:[1,0,1]
	v_lshlrev_b32_e32 v138, 16, v184
	v_and_b32_e32 v139, 0xffff0000, v184
	v_pk_fma_f32 v[122:123], v[122:123], 0.5, v[138:139] op_sel_hi:[1,0,1]
	v_lshlrev_b32_e32 v138, 16, v185
	v_and_b32_e32 v139, 0xffff0000, v185
	v_pk_fma_f32 v[124:125], v[124:125], 0.5, v[138:139] op_sel_hi:[1,0,1]
	v_cvt_pk_bf16_f32 v138, v126, v127
	v_cvt_pk_bf16_f32 v139, v128, v129
	v_cvt_pk_bf16_f32 v140, v122, v123
	s_and_b64 vcc, exec, s[8:9]
	v_cvt_pk_bf16_f32 v141, v124, v125
	global_store_dwordx4 v[234:235], v[138:141], off nt
	s_nop 1
	v_lshl_add_u64 v[138:139], v[142:143], 2, s[12:13]
	s_cbranch_vccnz .LBB0_327
	global_store_dwordx4 v[138:139], v[126:129], off
	global_store_dwordx4 v[138:139], v[122:125], off offset:16
.LBB0_327:
	v_lshlrev_b32_e32 v140, 16, v178
	v_and_b32_e32 v141, 0xffff0000, v178
	v_pk_fma_f32 v[118:119], v[118:119], 0.5, v[140:141] op_sel_hi:[1,0,1]
	v_lshlrev_b32_e32 v140, 16, v179
	v_and_b32_e32 v141, 0xffff0000, v179
	v_pk_fma_f32 v[120:121], v[120:121], 0.5, v[140:141] op_sel_hi:[1,0,1]
	v_lshlrev_b32_e32 v140, 16, v180
	v_and_b32_e32 v141, 0xffff0000, v180
	v_pk_fma_f32 v[110:111], v[110:111], 0.5, v[140:141] op_sel_hi:[1,0,1]
	v_lshlrev_b32_e32 v140, 16, v181
	v_and_b32_e32 v141, 0xffff0000, v181
	v_pk_fma_f32 v[112:113], v[112:113], 0.5, v[140:141] op_sel_hi:[1,0,1]
	s_and_b64 vcc, exec, s[8:9]
	v_cvt_pk_bf16_f32 v140, v118, v119
	v_cvt_pk_bf16_f32 v141, v120, v121
	v_cvt_pk_bf16_f32 v142, v110, v111
	v_cvt_pk_bf16_f32 v143, v112, v113
	global_store_dwordx4 v[234:235], v[140:143], off offset:64 nt
	s_cbranch_vccnz .LBB0_329
	global_store_dwordx4 v[138:139], v[118:121], off offset:128
	global_store_dwordx4 v[138:139], v[110:113], off offset:144

; #define GAS __attribute__((address_space(1)))
; DI unsigned cvtpk(float lo, float hi) { unsigned r; asm volatile("v_cvt_pk_bf16_f32 %0, %1, %2" : "=v"(r) : "v"(lo), "v"(hi)); return r; }
;     DI void operator()(const f32x4 (&acc)[2][2][4][2], const Unit& u, int wr, int wc, int fr, int fq) const {
;     ...
;             for (int m = 0; m < 4; ++m) {
;                 const int r = row0 + ai * HALF + m * 16; const size_t off = (size_t)r * DM + col0; float ss = 0.f;
; #pragma unroll
;                 for (int bj = 0; bj < 2; ++bj) {
;                     const u32x4 h = H[ai][m][bj];
;                     const f32x4 a0 = acc[ai][bj][m][0], a1 = acc[ai][bj][m][1];
;                     float v[8];
;                     v[0] = bflo(h.x) + a0[0] * scale; v[1] = bfhi(h.x) + a0[1] * scale;
;                     v[2] = bflo(h.y) + a0[2] * scale; v[3] = bfhi(h.y) + a0[3] * scale;
;                     v[4] = bflo(h.z) + a1[0] * scale; v[5] = bfhi(h.z) + a1[1] * scale;
;                     v[6] = bflo(h.w) + a1[2] * scale; v[7] = bfhi(h.w) + a1[3] * scale;
; #pragma unroll
;                     for (int e = 0; e < 8; ++e) ss += v[e] * v[e];
;                     u32x4 nh;
;                     nh.x = cvtpk(v[0], v[1]); nh.y = cvtpk(v[2], v[3]); nh.z = cvtpk(v[4], v[5]); nh.w = cvtpk(v[6], v[7]);
;                     *(GAS u32x4*)(hi + hbase + (size_t)r * 256 + bj * 32) = nh;
;                     if (out) { *(GAS f32x4*)(out + off + bj * 32) = (f32x4){v[0], v[1], v[2], v[3]}; *(GAS f32x4*)(out + off + bj * 32 + 4) = (f32x4){v[4], v[5], v[6], v[7]}; }
.LBB0_331:
	s_or_b64 exec, exec, s[20:21]
	v_lshlrev_b64 v[110:111], 11, v[232:233]
	v_lshl_add_u64 v[118:119], v[110:111], 0, v[212:213]
	v_lshlrev_b32_e32 v110, 16, v174
	v_and_b32_e32 v111, 0xffff0000, v174
	v_pk_fma_f32 v[102:103], v[102:103], 0.5, v[110:111] op_sel_hi:[1,0,1]
	v_lshlrev_b32_e32 v110, 16, v175
	v_and_b32_e32 v111, 0xffff0000, v175
	v_pk_fma_f32 v[104:105], v[104:105], 0.5, v[110:111] op_sel_hi:[1,0,1]
	v_lshlrev_b32_e32 v110, 16, v176
	v_and_b32_e32 v111, 0xffff0000, v176
	v_pk_fma_f32 v[98:99], v[98:99], 0.5, v[110:111] op_sel_hi:[1,0,1]
	v_lshlrev_b32_e32 v110, 16, v177
	v_and_b32_e32 v111, 0xffff0000, v177
	v_pk_fma_f32 v[100:101], v[100:101], 0.5, v[110:111] op_sel_hi:[1,0,1]
	v_cvt_pk_bf16_f32 v110, v102, v103
	v_cvt_pk_bf16_f32 v111, v104, v105
	v_cvt_pk_bf16_f32 v112, v98, v99
	s_and_b64 vcc, exec, s[8:9]
	v_cvt_pk_bf16_f32 v113, v100, v101
	global_store_dwordx4 v[230:231], v[110:113], off nt
	s_nop 1
	v_lshl_add_u64 v[110:111], v[118:119], 2, s[12:13]
	s_cbranch_vccnz .LBB0_333
	global_store_dwordx4 v[110:111], v[102:105], off
	global_store_dwordx4 v[110:111], v[98:101], off offset:16
.LBB0_333:
	v_lshlrev_b32_e32 v112, 16, v170
	v_and_b32_e32 v113, 0xffff0000, v170
	v_pk_fma_f32 v[90:91], v[90:91], 0.5, v[112:113] op_sel_hi:[1,0,1]
	v_lshlrev_b32_e32 v112, 16, v171
	v_and_b32_e32 v113, 0xffff0000, v171
	v_pk_fma_f32 v[92:93], v[92:93], 0.5, v[112:113] op_sel_hi:[1,0,1]
	v_lshlrev_b32_e32 v112, 16, v172
	v_and_b32_e32 v113, 0xffff0000, v172
	v_pk_fma_f32 v[86:87], v[86:87], 0.5, v[112:113] op_sel_hi:[1,0,1]
	v_lshlrev_b32_e32 v112, 16, v173
	v_and_b32_e32 v113, 0xffff0000, v173
	v_pk_fma_f32 v[88:89], v[88:89], 0.5, v[112:113] op_sel_hi:[1,0,1]
	s_and_b64 vcc, exec, s[8:9]
	v_cvt_pk_bf16_f32 v118, v90, v91
	v_cvt_pk_bf16_f32 v119, v92, v93
	v_cvt_pk_bf16_f32 v120, v86, v87
	v_cvt_pk_bf16_f32 v121, v88, v89
	global_store_dwordx4 v[230:231], v[118:121], off offset:64 nt
	s_cbranch_vccnz .LBB0_335
	global_store_dwordx4 v[110:111], v[90:93], off offset:128
	global_store_dwordx4 v[110:111], v[86:89], off offset:144

; #define GAS __attribute__((address_space(1)))
; DI unsigned cvtpk(float lo, float hi) { unsigned r; asm volatile("v_cvt_pk_bf16_f32 %0, %1, %2" : "=v"(r) : "v"(lo), "v"(hi)); return r; }
;     DI void operator()(const f32x4 (&acc)[2][2][4][2], const Unit& u, int wr, int wc, int fr, int fq) const {
;     ...
;             for (int m = 0; m < 4; ++m) {
;                 const int r = row0 + ai * HALF + m * 16; const size_t off = (size_t)r * DM + col0; float ss = 0.f;
; #pragma unroll
;                 for (int bj = 0; bj < 2; ++bj) {
;                     const u32x4 h = H[ai][m][bj];
;                     const f32x4 a0 = acc[ai][bj][m][0], a1 = acc[ai][bj][m][1];
;                     float v[8];
;                     v[0] = bflo(h.x) + a0[0] * scale; v[1] = bfhi(h.x) + a0[1] * scale;
;                     v[2] = bflo(h.y) + a0[2] * scale; v[3] = bfhi(h.y) + a0[3] * scale;
;                     v[4] = bflo(h.z) + a1[0] * scale; v[5] = bfhi(h.z) + a1[1] * scale;
;                     v[6] = bflo(h.w) + a1[2] * scale; v[7] = bfhi(h.w) + a1[3] * scale;
; #pragma unroll
;                     for (int e = 0; e < 8; ++e) ss += v[e] * v[e];
;                     u32x4 nh;
;                     nh.x = cvtpk(v[0], v[1]); nh.y = cvtpk(v[2], v[3]); nh.z = cvtpk(v[4], v[5]); nh.w = cvtpk(v[6], v[7]);
;                     *(GAS u32x4*)(hi + hbase + (size_t)r * 256 + bj * 32) = nh;
;                     if (out) { *(GAS f32x4*)(out + off + bj * 32) = (f32x4){v[0], v[1], v[2], v[3]}; *(GAS f32x4*)(out + off + bj * 32 + 4) = (f32x4){v[4], v[5], v[6], v[7]}; }
.LBB0_337:
	s_or_b64 exec, exec, s[20:21]
	v_lshlrev_b64 v[86:87], 11, v[228:229]
	v_lshl_add_u64 v[90:91], v[86:87], 0, v[212:213]
	v_lshlrev_b32_e32 v86, 16, v166
	v_and_b32_e32 v87, 0xffff0000, v166
	v_pk_fma_f32 v[78:79], v[78:79], 0.5, v[86:87] op_sel_hi:[1,0,1]
	v_lshlrev_b32_e32 v86, 16, v167
	v_and_b32_e32 v87, 0xffff0000, v167
	v_pk_fma_f32 v[80:81], v[80:81], 0.5, v[86:87] op_sel_hi:[1,0,1]
	v_lshlrev_b32_e32 v86, 16, v168
	v_and_b32_e32 v87, 0xffff0000, v168
	v_pk_fma_f32 v[74:75], v[74:75], 0.5, v[86:87] op_sel_hi:[1,0,1]
	v_lshlrev_b32_e32 v86, 16, v169
	v_and_b32_e32 v87, 0xffff0000, v169
	v_pk_fma_f32 v[76:77], v[76:77], 0.5, v[86:87] op_sel_hi:[1,0,1]
	v_cvt_pk_bf16_f32 v86, v78, v79
	v_cvt_pk_bf16_f32 v87, v80, v81
	v_cvt_pk_bf16_f32 v88, v74, v75
	s_and_b64 vcc, exec, s[8:9]
	v_cvt_pk_bf16_f32 v89, v76, v77
	global_store_dwordx4 v[226:227], v[86:89], off nt
	s_nop 1
	v_lshl_add_u64 v[86:87], v[90:91], 2, s[12:13]
	s_cbranch_vccnz .LBB0_339
	global_store_dwordx4 v[86:87], v[78:81], off
	global_store_dwordx4 v[86:87], v[74:77], off offset:16
.LBB0_339:
	v_lshlrev_b32_e32 v88, 16, v154
	v_and_b32_e32 v89, 0xffff0000, v154
	v_pk_fma_f32 v[70:71], v[70:71], 0.5, v[88:89] op_sel_hi:[1,0,1]
	v_lshlrev_b32_e32 v88, 16, v155
	v_and_b32_e32 v89, 0xffff0000, v155
	v_pk_fma_f32 v[72:73], v[72:73], 0.5, v[88:89] op_sel_hi:[1,0,1]
	v_lshlrev_b32_e32 v88, 16, v156
	v_and_b32_e32 v89, 0xffff0000, v156
	v_pk_fma_f32 v[66:67], v[66:67], 0.5, v[88:89] op_sel_hi:[1,0,1]
	v_lshlrev_b32_e32 v88, 16, v157
	v_and_b32_e32 v89, 0xffff0000, v157
	v_pk_fma_f32 v[68:69], v[68:69], 0.5, v[88:89] op_sel_hi:[1,0,1]
	s_and_b64 vcc, exec, s[8:9]
	v_cvt_pk_bf16_f32 v88, v70, v71
	v_cvt_pk_bf16_f32 v89, v72, v73
	v_cvt_pk_bf16_f32 v90, v66, v67
	v_cvt_pk_bf16_f32 v91, v68, v69
	global_store_dwordx4 v[226:227], v[88:91], off offset:64 nt
	s_cbranch_vccnz .LBB0_341
	global_store_dwordx4 v[86:87], v[70:73], off offset:128
	global_store_dwordx4 v[86:87], v[66:69], off offset:144

; #define GAS __attribute__((address_space(1)))
; DI unsigned cvtpk(float lo, float hi) { unsigned r; asm volatile("v_cvt_pk_bf16_f32 %0, %1, %2" : "=v"(r) : "v"(lo), "v"(hi)); return r; }
;     DI void operator()(const f32x4 (&acc)[2][2][4][2], const Unit& u, int wr, int wc, int fr, int fq) const {
;     ...
;             for (int m = 0; m < 4; ++m) {
;                 const int r = row0 + ai * HALF + m * 16; const size_t off = (size_t)r * DM + col0; float ss = 0.f;
; #pragma unroll
;                 for (int bj = 0; bj < 2; ++bj) {
;                     const u32x4 h = H[ai][m][bj];
;                     const f32x4 a0 = acc[ai][bj][m][0], a1 = acc[ai][bj][m][1];
;                     float v[8];
;                     v[0] = bflo(h.x) + a0[0] * scale; v[1] = bfhi(h.x) + a0[1] * scale;
;                     v[2] = bflo(h.y) + a0[2] * scale; v[3] = bfhi(h.y) + a0[3] * scale;
;                     v[4] = bflo(h.z) + a1[0] * scale; v[5] = bfhi(h.z) + a1[1] * scale;
;                     v[6] = bflo(h.w) + a1[2] * scale; v[7] = bfhi(h.w) + a1[3] * scale;
; #pragma unroll
;                     for (int e = 0; e < 8; ++e) ss += v[e] * v[e];
;                     u32x4 nh;
;                     nh.x = cvtpk(v[0], v[1]); nh.y = cvtpk(v[2], v[3]); nh.z = cvtpk(v[4], v[5]); nh.w = cvtpk(v[6], v[7]);
;                     *(GAS u32x4*)(hi + hbase + (size_t)r * 256 + bj * 32) = nh;
;                     if (out) { *(GAS f32x4*)(out + off + bj * 32) = (f32x4){v[0], v[1], v[2], v[3]}; *(GAS f32x4*)(out + off + bj * 32 + 4) = (f32x4){v[4], v[5], v[6], v[7]}; }
.LBB0_343:
	s_or_b64 exec, exec, s[20:21]
	v_lshlrev_b64 v[66:67], 11, v[224:225]
	v_lshl_add_u64 v[70:71], v[66:67], 0, v[212:213]
	v_lshlrev_b32_e32 v66, 16, v150
	v_and_b32_e32 v67, 0xffff0000, v150
	v_pk_fma_f32 v[62:63], v[62:63], 0.5, v[66:67] op_sel_hi:[1,0,1]
	v_lshlrev_b32_e32 v66, 16, v151
	v_and_b32_e32 v67, 0xffff0000, v151
	v_pk_fma_f32 v[64:65], v[64:65], 0.5, v[66:67] op_sel_hi:[1,0,1]
	v_lshlrev_b32_e32 v66, 16, v152
	v_and_b32_e32 v67, 0xffff0000, v152
	v_pk_fma_f32 v[58:59], v[58:59], 0.5, v[66:67] op_sel_hi:[1,0,1]
	v_lshlrev_b32_e32 v66, 16, v153
	v_and_b32_e32 v67, 0xffff0000, v153
	v_pk_fma_f32 v[60:61], v[60:61], 0.5, v[66:67] op_sel_hi:[1,0,1]
	v_cvt_pk_bf16_f32 v66, v62, v63
	v_cvt_pk_bf16_f32 v67, v64, v65
	v_cvt_pk_bf16_f32 v68, v58, v59
	s_and_b64 vcc, exec, s[8:9]
	v_cvt_pk_bf16_f32 v69, v60, v61
	global_store_dwordx4 v[222:223], v[66:69], off nt
	s_nop 1
	v_lshl_add_u64 v[66:67], v[70:71], 2, s[12:13]
	s_cbranch_vccnz .LBB0_345
	global_store_dwordx4 v[66:67], v[62:65], off
	global_store_dwordx4 v[66:67], v[58:61], off offset:16
.LBB0_345:
	v_lshlrev_b32_e32 v68, 16, v146
	v_and_b32_e32 v69, 0xffff0000, v146
	v_pk_fma_f32 v[54:55], v[54:55], 0.5, v[68:69] op_sel_hi:[1,0,1]
	v_lshlrev_b32_e32 v68, 16, v147
	v_and_b32_e32 v69, 0xffff0000, v147
	v_pk_fma_f32 v[56:57], v[56:57], 0.5, v[68:69] op_sel_hi:[1,0,1]
	v_lshlrev_b32_e32 v68, 16, v148
	v_and_b32_e32 v69, 0xffff0000, v148
	v_pk_fma_f32 v[50:51], v[50:51], 0.5, v[68:69] op_sel_hi:[1,0,1]
	v_lshlrev_b32_e32 v68, 16, v149
	v_and_b32_e32 v69, 0xffff0000, v149
	v_pk_fma_f32 v[52:53], v[52:53], 0.5, v[68:69] op_sel_hi:[1,0,1]
	s_and_b64 vcc, exec, s[8:9]
	v_cvt_pk_bf16_f32 v68, v54, v55
	v_cvt_pk_bf16_f32 v69, v56, v57
	v_cvt_pk_bf16_f32 v70, v50, v51
	v_cvt_pk_bf16_f32 v71, v52, v53
	global_store_dwordx4 v[222:223], v[68:71], off offset:64 nt
	s_cbranch_vccnz .LBB0_347
	global_store_dwordx4 v[66:67], v[54:57], off offset:128
	global_store_dwordx4 v[66:67], v[50:53], off offset:144

; #define GAS __attribute__((address_space(1)))
; DI unsigned cvtpk(float lo, float hi) { unsigned r; asm volatile("v_cvt_pk_bf16_f32 %0, %1, %2" : "=v"(r) : "v"(lo), "v"(hi)); return r; }
;     DI void operator()(const f32x4 (&acc)[2][2][4][2], const Unit& u, int wr, int wc, int fr, int fq) const {
;     ...
;             for (int m = 0; m < 4; ++m) {
;                 const int r = row0 + ai * HALF + m * 16; const size_t off = (size_t)r * DM + col0; float ss = 0.f;
; #pragma unroll
;                 for (int bj = 0; bj < 2; ++bj) {
;                     const u32x4 h = H[ai][m][bj];
;                     const f32x4 a0 = acc[ai][bj][m][0], a1 = acc[ai][bj][m][1];
;                     float v[8];
;                     v[0] = bflo(h.x) + a0[0] * scale; v[1] = bfhi(h.x) + a0[1] * scale;
;                     v[2] = bflo(h.y) + a0[2] * scale; v[3] = bfhi(h.y) + a0[3] * scale;
;                     v[4] = bflo(h.z) + a1[0] * scale; v[5] = bfhi(h.z) + a1[1] * scale;
;                     v[6] = bflo(h.w) + a1[2] * scale; v[7] = bfhi(h.w) + a1[3] * scale;
; #pragma unroll
;                     for (int e = 0; e < 8; ++e) ss += v[e] * v[e];
;                     u32x4 nh;
;                     nh.x = cvtpk(v[0], v[1]); nh.y = cvtpk(v[2], v[3]); nh.z = cvtpk(v[4], v[5]); nh.w = cvtpk(v[6], v[7]);
;                     *(GAS u32x4*)(hi + hbase + (size_t)r * 256 + bj * 32) = nh;
;                     if (out) { *(GAS f32x4*)(out + off + bj * 32) = (f32x4){v[0], v[1], v[2], v[3]}; *(GAS f32x4*)(out + off + bj * 32 + 4) = (f32x4){v[4], v[5], v[6], v[7]}; }
.LBB0_349:
	s_or_b64 exec, exec, s[20:21]
	v_lshlrev_b64 v[50:51], 11, v[220:221]
	v_lshl_add_u64 v[54:55], v[50:51], 0, v[212:213]
	v_lshlrev_b32_e32 v50, 16, v134
	v_and_b32_e32 v51, 0xffff0000, v134
	v_pk_fma_f32 v[46:47], v[46:47], 0.5, v[50:51] op_sel_hi:[1,0,1]
	v_lshlrev_b32_e32 v50, 16, v135
	v_and_b32_e32 v51, 0xffff0000, v135
	v_pk_fma_f32 v[48:49], v[48:49], 0.5, v[50:51] op_sel_hi:[1,0,1]
	v_lshlrev_b32_e32 v50, 16, v136
	v_and_b32_e32 v51, 0xffff0000, v136
	v_pk_fma_f32 v[42:43], v[42:43], 0.5, v[50:51] op_sel_hi:[1,0,1]
	v_lshlrev_b32_e32 v50, 16, v137
	v_and_b32_e32 v51, 0xffff0000, v137
	v_pk_fma_f32 v[44:45], v[44:45], 0.5, v[50:51] op_sel_hi:[1,0,1]
	v_cvt_pk_bf16_f32 v50, v46, v47
	v_cvt_pk_bf16_f32 v51, v48, v49
	v_cvt_pk_bf16_f32 v52, v42, v43
	s_and_b64 vcc, exec, s[8:9]
	v_cvt_pk_bf16_f32 v53, v44, v45
	global_store_dwordx4 v[218:219], v[50:53], off nt
	s_nop 1
	v_lshl_add_u64 v[50:51], v[54:55], 2, s[12:13]
	s_cbranch_vccnz .LBB0_351
	global_store_dwordx4 v[50:51], v[46:49], off
	global_store_dwordx4 v[50:51], v[42:45], off offset:16
.LBB0_351:
	v_lshlrev_b32_e32 v52, 16, v130
	v_and_b32_e32 v53, 0xffff0000, v130
	v_pk_fma_f32 v[38:39], v[38:39], 0.5, v[52:53] op_sel_hi:[1,0,1]
	v_lshlrev_b32_e32 v52, 16, v131
	v_and_b32_e32 v53, 0xffff0000, v131
	v_pk_fma_f32 v[40:41], v[40:41], 0.5, v[52:53] op_sel_hi:[1,0,1]
	v_lshlrev_b32_e32 v52, 16, v132
	v_and_b32_e32 v53, 0xffff0000, v132
	v_pk_fma_f32 v[34:35], v[34:35], 0.5, v[52:53] op_sel_hi:[1,0,1]
	v_lshlrev_b32_e32 v52, 16, v133
	v_and_b32_e32 v53, 0xffff0000, v133
	v_pk_fma_f32 v[36:37], v[36:37], 0.5, v[52:53] op_sel_hi:[1,0,1]
	s_and_b64 vcc, exec, s[8:9]
	v_cvt_pk_bf16_f32 v52, v38, v39
	v_cvt_pk_bf16_f32 v53, v40, v41
	v_cvt_pk_bf16_f32 v54, v34, v35
	v_cvt_pk_bf16_f32 v55, v36, v37
	global_store_dwordx4 v[218:219], v[52:55], off offset:64 nt
	s_cbranch_vccnz .LBB0_353
	global_store_dwordx4 v[50:51], v[38:41], off offset:128
	global_store_dwordx4 v[50:51], v[34:37], off offset:144

; #define GAS __attribute__((address_space(1)))
; DI unsigned cvtpk(float lo, float hi) { unsigned r; asm volatile("v_cvt_pk_bf16_f32 %0, %1, %2" : "=v"(r) : "v"(lo), "v"(hi)); return r; }
;     DI void operator()(const f32x4 (&acc)[2][2][4][2], const Unit& u, int wr, int wc, int fr, int fq) const {
;     ...
;             for (int m = 0; m < 4; ++m) {
;                 const int r = row0 + ai * HALF + m * 16; const size_t off = (size_t)r * DM + col0; float ss = 0.f;
; #pragma unroll
;                 for (int bj = 0; bj < 2; ++bj) {
;                     const u32x4 h = H[ai][m][bj];
;                     const f32x4 a0 = acc[ai][bj][m][0], a1 = acc[ai][bj][m][1];
;                     float v[8];
;                     v[0] = bflo(h.x) + a0[0] * scale; v[1] = bfhi(h.x) + a0[1] * scale;
;                     v[2] = bflo(h.y) + a0[2] * scale; v[3] = bfhi(h.y) + a0[3] * scale;
;                     v[4] = bflo(h.z) + a1[0] * scale; v[5] = bfhi(h.z) + a1[1] * scale;
;                     v[6] = bflo(h.w) + a1[2] * scale; v[7] = bfhi(h.w) + a1[3] * scale;
; #pragma unroll
;                     for (int e = 0; e < 8; ++e) ss += v[e] * v[e];
;                     u32x4 nh;
;                     nh.x = cvtpk(v[0], v[1]); nh.y = cvtpk(v[2], v[3]); nh.z = cvtpk(v[4], v[5]); nh.w = cvtpk(v[6], v[7]);
;                     *(GAS u32x4*)(hi + hbase + (size_t)r * 256 + bj * 32) = nh;
;                     if (out) { *(GAS f32x4*)(out + off + bj * 32) = (f32x4){v[0], v[1], v[2], v[3]}; *(GAS f32x4*)(out + off + bj * 32 + 4) = (f32x4){v[4], v[5], v[6], v[7]}; }
.LBB0_355:
	s_or_b64 exec, exec, s[20:21]
	v_lshlrev_b64 v[34:35], 11, v[216:217]
	v_lshl_add_u64 v[38:39], v[34:35], 0, v[212:213]
	v_lshlrev_b32_e32 v34, 16, v114
	v_and_b32_e32 v35, 0xffff0000, v114
	v_pk_fma_f32 v[30:31], v[30:31], 0.5, v[34:35] op_sel_hi:[1,0,1]
	v_lshlrev_b32_e32 v34, 16, v115
	v_and_b32_e32 v35, 0xffff0000, v115
	v_pk_fma_f32 v[32:33], v[32:33], 0.5, v[34:35] op_sel_hi:[1,0,1]
	v_lshlrev_b32_e32 v34, 16, v116
	v_and_b32_e32 v35, 0xffff0000, v116
	v_pk_fma_f32 v[26:27], v[26:27], 0.5, v[34:35] op_sel_hi:[1,0,1]
	v_lshlrev_b32_e32 v34, 16, v117
	v_and_b32_e32 v35, 0xffff0000, v117
	v_pk_fma_f32 v[28:29], v[28:29], 0.5, v[34:35] op_sel_hi:[1,0,1]
	v_cvt_pk_bf16_f32 v34, v30, v31
	v_cvt_pk_bf16_f32 v35, v32, v33
	v_cvt_pk_bf16_f32 v36, v26, v27
	s_and_b64 vcc, exec, s[8:9]
	v_cvt_pk_bf16_f32 v37, v28, v29
	global_store_dwordx4 v[214:215], v[34:37], off nt
	s_nop 1
	v_lshl_add_u64 v[34:35], v[38:39], 2, s[12:13]
	s_cbranch_vccnz .LBB0_357
	global_store_dwordx4 v[34:35], v[30:33], off
	global_store_dwordx4 v[34:35], v[26:29], off offset:16
.LBB0_357:
	v_lshlrev_b32_e32 v36, 16, v106
	v_and_b32_e32 v37, 0xffff0000, v106
	v_pk_fma_f32 v[22:23], v[22:23], 0.5, v[36:37] op_sel_hi:[1,0,1]
	v_lshlrev_b32_e32 v36, 16, v107
	v_and_b32_e32 v37, 0xffff0000, v107
	v_pk_fma_f32 v[24:25], v[24:25], 0.5, v[36:37] op_sel_hi:[1,0,1]
	v_lshlrev_b32_e32 v36, 16, v108
	v_and_b32_e32 v37, 0xffff0000, v108
	v_pk_fma_f32 v[18:19], v[18:19], 0.5, v[36:37] op_sel_hi:[1,0,1]
	v_lshlrev_b32_e32 v36, 16, v109
	v_and_b32_e32 v37, 0xffff0000, v109
	v_pk_fma_f32 v[20:21], v[20:21], 0.5, v[36:37] op_sel_hi:[1,0,1]
	s_and_b64 vcc, exec, s[8:9]
	v_cvt_pk_bf16_f32 v36, v22, v23
	v_cvt_pk_bf16_f32 v37, v24, v25
	v_cvt_pk_bf16_f32 v38, v18, v19
	v_cvt_pk_bf16_f32 v39, v20, v21
	global_store_dwordx4 v[214:215], v[36:39], off offset:64 nt
	s_cbranch_vccnz .LBB0_359
	global_store_dwordx4 v[34:35], v[22:25], off offset:128
	global_store_dwordx4 v[34:35], v[18:21], off offset:144

; #define GAS __attribute__((address_space(1)))
; DI unsigned cvtpk(float lo, float hi) { unsigned r; asm volatile("v_cvt_pk_bf16_f32 %0, %1, %2" : "=v"(r) : "v"(lo), "v"(hi)); return r; }
;     DI void operator()(const f32x4 (&acc)[2][2][4][2], const Unit& u, int wr, int wc, int fr, int fq) const {
;     ...
;             for (int m = 0; m < 4; ++m) {
;                 const int r = row0 + ai * HALF + m * 16; const size_t off = (size_t)r * DM + col0; float ss = 0.f;
; #pragma unroll
;                 for (int bj = 0; bj < 2; ++bj) {
;                     const u32x4 h = H[ai][m][bj];
;                     const f32x4 a0 = acc[ai][bj][m][0], a1 = acc[ai][bj][m][1];
;                     float v[8];
;                     v[0] = bflo(h.x) + a0[0] * scale; v[1] = bfhi(h.x) + a0[1] * scale;
;                     v[2] = bflo(h.y) + a0[2] * scale; v[3] = bfhi(h.y) + a0[3] * scale;
;                     v[4] = bflo(h.z) + a1[0] * scale; v[5] = bfhi(h.z) + a1[1] * scale;
;                     v[6] = bflo(h.w) + a1[2] * scale; v[7] = bfhi(h.w) + a1[3] * scale;
; #pragma unroll
;                     for (int e = 0; e < 8; ++e) ss += v[e] * v[e];
;                     u32x4 nh;
;                     nh.x = cvtpk(v[0], v[1]); nh.y = cvtpk(v[2], v[3]); nh.z = cvtpk(v[4], v[5]); nh.w = cvtpk(v[6], v[7]);
;                     *(GAS u32x4*)(hi + hbase + (size_t)r * 256 + bj * 32) = nh;
;                     if (out) { *(GAS f32x4*)(out + off + bj * 32) = (f32x4){v[0], v[1], v[2], v[3]}; *(GAS f32x4*)(out + off + bj * 32 + 4) = (f32x4){v[4], v[5], v[6], v[7]}; }
.LBB0_361:
	s_or_b64 exec, exec, s[20:21]
	v_lshlrev_b64 v[18:19], 11, v[210:211]
	v_lshl_add_u64 v[22:23], v[18:19], 0, v[212:213]
	v_lshlrev_b32_e32 v18, 16, v94
	v_and_b32_e32 v19, 0xffff0000, v94
	v_pk_fma_f32 v[14:15], v[14:15], 0.5, v[18:19] op_sel_hi:[1,0,1]
	v_lshlrev_b32_e32 v18, 16, v95
	v_and_b32_e32 v19, 0xffff0000, v95
	v_pk_fma_f32 v[16:17], v[16:17], 0.5, v[18:19] op_sel_hi:[1,0,1]
	v_lshlrev_b32_e32 v18, 16, v96
	v_and_b32_e32 v19, 0xffff0000, v96
	v_pk_fma_f32 v[10:11], v[10:11], 0.5, v[18:19] op_sel_hi:[1,0,1]
	v_lshlrev_b32_e32 v18, 16, v97
	v_and_b32_e32 v19, 0xffff0000, v97
	v_pk_fma_f32 v[12:13], v[12:13], 0.5, v[18:19] op_sel_hi:[1,0,1]
	v_cvt_pk_bf16_f32 v18, v14, v15
	v_cvt_pk_bf16_f32 v19, v16, v17
	v_cvt_pk_bf16_f32 v20, v10, v11
	s_and_b64 vcc, exec, s[8:9]
	v_cvt_pk_bf16_f32 v21, v12, v13
	global_store_dwordx4 v[208:209], v[18:21], off nt
	s_nop 1
	v_lshl_add_u64 v[18:19], v[22:23], 2, s[12:13]
	s_cbranch_vccnz .LBB0_363
	global_store_dwordx4 v[18:19], v[14:17], off
	global_store_dwordx4 v[18:19], v[10:13], off offset:16
.LBB0_363:
	v_lshlrev_b32_e32 v20, 16, v82
	v_and_b32_e32 v21, 0xffff0000, v82
	v_pk_fma_f32 v[6:7], v[6:7], 0.5, v[20:21] op_sel_hi:[1,0,1]
	v_lshlrev_b32_e32 v20, 16, v83
	v_and_b32_e32 v21, 0xffff0000, v83
	v_pk_fma_f32 v[8:9], v[8:9], 0.5, v[20:21] op_sel_hi:[1,0,1]
	v_lshlrev_b32_e32 v20, 16, v84
	v_and_b32_e32 v21, 0xffff0000, v84
	v_pk_fma_f32 v[2:3], v[2:3], 0.5, v[20:21] op_sel_hi:[1,0,1]
	v_lshlrev_b32_e32 v20, 16, v85
	v_and_b32_e32 v21, 0xffff0000, v85
	v_pk_fma_f32 v[4:5], v[4:5], 0.5, v[20:21] op_sel_hi:[1,0,1]
	s_and_b64 vcc, exec, s[8:9]
	v_cvt_pk_bf16_f32 v20, v6, v7
	v_cvt_pk_bf16_f32 v21, v8, v9
	v_cvt_pk_bf16_f32 v22, v2, v3
	v_cvt_pk_bf16_f32 v23, v4, v5
	global_store_dwordx4 v[208:209], v[20:23], off offset:64 nt
	s_cbranch_vccnz .LBB0_365
	global_store_dwordx4 v[18:19], v[6:9], off offset:128
	global_store_dwordx4 v[18:19], v[2:5], off offset:144

; #define PG8_STAGE(bufoff, gbase, voff) do { _Pragma("unroll") for (int _i = 0; _i < 2; ++_i) \
;         __builtin_amdgcn_global_load_lds((const unsigned*)((const char*)(gbase) + (voff)[_i]), (LAS unsigned*)(lds + (bufoff) + ldsw + _i * 8192), 16, 0, 0); } while (0)
; #define PG8_LDA(dst, b, h) do { _Pragma("unroll") for (int m = 0; m < 4; ++m) _Pragma("unroll") for (int k = 0; k < 2; ++k) dst[m][k] = *(const LAS bf16x8*)(lds + PG8_SA(b, h) + aoff + m * 2048 + k * 1024); } while (0)
; #define PG8_LDB(dst, b, h) do { _Pragma("unroll") for (int n = 0; n < 2; ++n) _Pragma("unroll") for (int k = 0; k < 2; ++k) dst[n][k] = *(const LAS bf16x8*)(lds + PG8_SB(b, h) + boff + n * 2048 + k * 1024); } while (0)
; #define PG8_MMA(ai, bj, At, Bt) do { __builtin_amdgcn_s_setprio(1); _Pragma("unroll") for (int m = 0; m < 4; ++m) _Pragma("unroll") for (int n = 0; n < 2; ++n) _Pragma("unroll") for (int k = 0; k < 2; ++k) \
;         acc[ai][bj][m][n] = __builtin_amdgcn_mfma_f32_16x16x32_bf16(Bt[n][k], At[m][k], acc[ai][bj][m][n], 0, 0, 0); __builtin_amdgcn_s_setprio(0); } while (0)
; #define PG8_WAIT_V(n) asm volatile("s_waitcnt vmcnt(" #n ")" ::: "memory")
; #define PG8_BAR __builtin_amdgcn_s_barrier()
; template <class Epi, class Sched, int KC, bool ALIGN_EPI = false, bool SP2 = false, bool ATILED = false>
; __device__ __forceinline__ void gemm_phase(LAS unsigned char* lds, const Gemm g, const Sched& S, const Epi& E, int wave_s) {
;     ...
;         for (int t = 0; t < nt; t += 2) {
;             const bool last = (t == nt - 2);
;             const char* a1 = cA + PG8_AOFF(t + 1);
;             const char* a2 = last ? nA : cA + PG8_AOFF(t + 2); const char* b2 = last ? nB : cB + (size_t)(t + 2) * kstep;
;             const char* a3 = a2 + kstep; const char* b3 = b2 + kstep;
;             if (last && has_next) S.a_ready(nxt);
;             if constexpr (SP2) {
;             PG8_LDB(B0, 0, 0); PG8_LDB(B1, 0, 1); PG8_SCHED; PG8_LDA(At, 0, 0); PG8_STAGE(PG8_SA(1, 1), a1 + hstepA, voffA);
;             PG8_WAIT_V(8); PG8_WAIT_L(0); PG8_BAR; PG8_MMA(0, 0, At, B0); PG8_MMA(0, 1, At, B1); PG8_BAR; PG8_SCHED;
;             PG8_LDA(At, 0, 1); PG8_STAGE(PG8_SB(0, 0), b2, voffB); PG8_STAGE(PG8_SB(0, 1), b2 + hstepB, voffB); PG8_STAGE(PG8_SA(0, 0), a2, voffA);
;             PG8_WAIT_V(8); PG8_WAIT_L(0); PG8_BAR; PG8_MMA(1, 0, At, B0); PG8_MMA(1, 1, At, B1); PG8_BAR; PG8_SCHED;
.LBB0_1021:
	s_add_u32 s20, s18, 0xfff80080
	s_addc_u32 s21, s19, -1
	s_add_i32 s49, 0, 0x10000
	s_cmp_eq_u32 s48, 28
	s_cselect_b32 s23, s9, s21
	s_cselect_b32 s22, s15, s20
	s_cselect_b32 s21, s3, s47
	s_cselect_b32 s20, s17, s46
	s_add_i32 s52, 0, 0x14000
	v_add_u32_e32 v142, s49, v229
	v_add_u32_e32 v158, s52, v229
	ds_read_b128 v[130:133], v142
	ds_read_b128 v[134:137], v142 offset:1024
	ds_read_b128 v[138:141], v142 offset:2048
	ds_read_b128 v[142:145], v142 offset:3072
	ds_read_b128 v[146:149], v158
	ds_read_b128 v[150:153], v158 offset:1024
	ds_read_b128 v[154:157], v158 offset:2048
	ds_read_b128 v[158:161], v158 offset:3072
	s_add_i32 m0, s34, 0xc000
	ds_read_b128 v[162:165], v230
	ds_read_b128 v[166:169], v230 offset:1024
	ds_read_b128 v[170:173], v230 offset:2048
	ds_read_b128 v[174:177], v230 offset:3072
	ds_read_b128 v[178:181], v230 offset:4096
	ds_read_b128 v[182:185], v230 offset:5120
	ds_read_b128 v[186:189], v230 offset:6144
	ds_read_b128 v[190:193], v230 offset:7168
	global_load_lds_dwordx4 v208, s[18:19]
	s_add_i32 m0, s34, 0xe000
	s_nop 0
	global_load_lds_dwordx4 v206, s[18:19]
	s_waitcnt vmcnt(8)
	s_waitcnt lgkmcnt(0)
	s_barrier
	s_waitcnt lgkmcnt(0)
	v_mfma_f32_16x16x32_bf16 v[126:129], v[130:133], v[162:165], v[126:129]
	v_mfma_f32_16x16x32_bf16 v[122:125], v[138:141], v[162:165], v[122:125]
	v_mfma_f32_16x16x32_bf16 v[110:113], v[130:133], v[170:173], v[110:113]
	v_mfma_f32_16x16x32_bf16 v[106:109], v[138:141], v[170:173], v[106:109]
	v_mfma_f32_16x16x32_bf16 v[94:97], v[130:133], v[178:181], v[94:97]
	v_mfma_f32_16x16x32_bf16 v[90:93], v[138:141], v[178:181], v[90:93]
	v_mfma_f32_16x16x32_bf16 v[78:81], v[130:133], v[186:189], v[78:81]
	v_mfma_f32_16x16x32_bf16 v[74:77], v[138:141], v[186:189], v[74:77]
	v_mfma_f32_16x16x32_bf16 v[126:129], v[134:137], v[166:169], v[126:129]
	v_mfma_f32_16x16x32_bf16 v[122:125], v[142:145], v[166:169], v[122:125]
	v_mfma_f32_16x16x32_bf16 v[110:113], v[134:137], v[174:177], v[110:113]
	v_mfma_f32_16x16x32_bf16 v[106:109], v[142:145], v[174:177], v[106:109]
	v_mfma_f32_16x16x32_bf16 v[94:97], v[134:137], v[182:185], v[94:97]
	v_mfma_f32_16x16x32_bf16 v[90:93], v[142:145], v[182:185], v[90:93]
	v_mfma_f32_16x16x32_bf16 v[78:81], v[134:137], v[190:193], v[78:81]
	v_mfma_f32_16x16x32_bf16 v[74:77], v[142:145], v[190:193], v[74:77]
	v_mfma_f32_16x16x32_bf16 v[118:121], v[146:149], v[162:165], v[118:121]
	v_mfma_f32_16x16x32_bf16 v[114:117], v[154:157], v[162:165], v[114:117]
	v_mfma_f32_16x16x32_bf16 v[102:105], v[146:149], v[170:173], v[102:105]
	v_mfma_f32_16x16x32_bf16 v[98:101], v[154:157], v[170:173], v[98:101]
	v_mfma_f32_16x16x32_bf16 v[86:89], v[146:149], v[178:181], v[86:89]
	v_mfma_f32_16x16x32_bf16 v[82:85], v[154:157], v[178:181], v[82:85]
	v_mfma_f32_16x16x32_bf16 v[70:73], v[146:149], v[186:189], v[70:73]
	v_mfma_f32_16x16x32_bf16 v[66:69], v[154:157], v[186:189], v[66:69]
	v_mfma_f32_16x16x32_bf16 v[118:121], v[150:153], v[166:169], v[118:121]
	v_mfma_f32_16x16x32_bf16 v[114:117], v[158:161], v[166:169], v[114:117]
	v_mfma_f32_16x16x32_bf16 v[102:105], v[150:153], v[174:177], v[102:105]
	v_mfma_f32_16x16x32_bf16 v[98:101], v[158:161], v[174:177], v[98:101]
	v_mfma_f32_16x16x32_bf16 v[86:89], v[150:153], v[182:185], v[86:89]
	v_mfma_f32_16x16x32_bf16 v[82:85], v[158:161], v[182:185], v[82:85]
	v_mfma_f32_16x16x32_bf16 v[70:73], v[150:153], v[190:193], v[70:73]
	v_mfma_f32_16x16x32_bf16 v[66:69], v[158:161], v[190:193], v[66:69]
	s_barrier
	s_add_u32 s100, s22, 0x80
	s_addc_u32 s101, s23, 0
	s_add_i32 s49, s49, s31
	s_mov_b32 m0, s49
	ds_read_b128 v[162:165], v230 offset:16384
	ds_read_b128 v[166:169], v230 offset:17408
	ds_read_b128 v[170:173], v230 offset:18432
	ds_read_b128 v[174:177], v230 offset:19456
	ds_read_b128 v[178:181], v230 offset:20480
	ds_read_b128 v[182:185], v230 offset:21504
	ds_read_b128 v[186:189], v230 offset:22528
	ds_read_b128 v[190:193], v230 offset:23552
	global_load_lds_dwordx4 v0, s[20:21]
	s_add_i32 m0, s49, 0x2000
	s_add_u32 s50, s20, 0x20000
	s_addc_u32 s51, s21, 0
	s_add_i32 s49, s52, s31
	global_load_lds_dwordx4 v202, s[20:21]
	s_mov_b32 m0, s49
	s_nop 0
	global_load_lds_dwordx4 v0, s[50:51]
	s_add_i32 m0, s49, 0x2000
	s_nop 0
	global_load_lds_dwordx4 v202, s[50:51]
	s_mov_b32 m0, s34
	s_nop 0
	global_load_lds_dwordx4 v198, s[22:23]
	s_mov_b32 m0, s35
	s_nop 0
	global_load_lds_dwordx4 v200, s[22:23]
	s_waitcnt vmcnt(8)
	s_waitcnt lgkmcnt(0)
	s_barrier
	s_waitcnt lgkmcnt(0)
	v_mfma_f32_16x16x32_bf16 v[62:65], v[130:133], v[162:165], v[62:65]
	v_mfma_f32_16x16x32_bf16 v[58:61], v[138:141], v[162:165], v[58:61]
	v_mfma_f32_16x16x32_bf16 v[46:49], v[130:133], v[170:173], v[46:49]
	v_mfma_f32_16x16x32_bf16 v[42:45], v[138:141], v[170:173], v[42:45]
	v_mfma_f32_16x16x32_bf16 v[30:33], v[130:133], v[178:181], v[30:33]
	v_mfma_f32_16x16x32_bf16 v[26:29], v[138:141], v[178:181], v[26:29]
	v_mfma_f32_16x16x32_bf16 v[14:17], v[130:133], v[186:189], v[14:17]
	v_mfma_f32_16x16x32_bf16 v[10:13], v[138:141], v[186:189], v[10:13]
	v_mfma_f32_16x16x32_bf16 v[62:65], v[134:137], v[166:169], v[62:65]
	v_mfma_f32_16x16x32_bf16 v[58:61], v[142:145], v[166:169], v[58:61]
	v_mfma_f32_16x16x32_bf16 v[46:49], v[134:137], v[174:177], v[46:49]
	v_mfma_f32_16x16x32_bf16 v[42:45], v[142:145], v[174:177], v[42:45]
	v_mfma_f32_16x16x32_bf16 v[30:33], v[134:137], v[182:185], v[30:33]
	v_mfma_f32_16x16x32_bf16 v[26:29], v[142:145], v[182:185], v[26:29]
	v_mfma_f32_16x16x32_bf16 v[14:17], v[134:137], v[190:193], v[14:17]
	v_mfma_f32_16x16x32_bf16 v[10:13], v[142:145], v[190:193], v[10:13]
	v_mfma_f32_16x16x32_bf16 v[54:57], v[146:149], v[162:165], v[54:57]
	v_mfma_f32_16x16x32_bf16 v[50:53], v[154:157], v[162:165], v[50:53]
	v_mfma_f32_16x16x32_bf16 v[38:41], v[146:149], v[170:173], v[38:41]
	v_mfma_f32_16x16x32_bf16 v[34:37], v[154:157], v[170:173], v[34:37]
	v_mfma_f32_16x16x32_bf16 v[22:25], v[146:149], v[178:181], v[22:25]
	v_mfma_f32_16x16x32_bf16 v[18:21], v[154:157], v[178:181], v[18:21]
	v_mfma_f32_16x16x32_bf16 v[6:9], v[146:149], v[186:189], v[6:9]
	v_mfma_f32_16x16x32_bf16 v[2:5], v[154:157], v[186:189], v[2:5]
	v_mfma_f32_16x16x32_bf16 v[54:57], v[150:153], v[166:169], v[54:57]
	v_mfma_f32_16x16x32_bf16 v[50:53], v[158:161], v[166:169], v[50:53]
	v_mfma_f32_16x16x32_bf16 v[38:41], v[150:153], v[174:177], v[38:41]
	v_mfma_f32_16x16x32_bf16 v[34:37], v[158:161], v[174:177], v[34:37]
	v_mfma_f32_16x16x32_bf16 v[22:25], v[150:153], v[182:185], v[22:25]
	v_mfma_f32_16x16x32_bf16 v[18:21], v[158:161], v[182:185], v[18:21]
	v_mfma_f32_16x16x32_bf16 v[6:9], v[150:153], v[190:193], v[6:9]
	v_mfma_f32_16x16x32_bf16 v[2:5], v[158:161], v[190:193], v[2:5]
	s_barrier
; #define PG8_STAGE(bufoff, gbase, voff) do { _Pragma("unroll") for (int _i = 0; _i < 2; ++_i) \
;         __builtin_amdgcn_global_load_lds((const unsigned*)((const char*)(gbase) + (voff)[_i]), (LAS unsigned*)(lds + (bufoff) + ldsw + _i * 8192), 16, 0, 0); } while (0)
; #define PG8_LDA(dst, b, h) do { _Pragma("unroll") for (int m = 0; m < 4; ++m) _Pragma("unroll") for (int k = 0; k < 2; ++k) dst[m][k] = *(const LAS bf16x8*)(lds + PG8_SA(b, h) + aoff + m * 2048 + k * 1024); } while (0)
; #define PG8_LDB(dst, b, h) do { _Pragma("unroll") for (int n = 0; n < 2; ++n) _Pragma("unroll") for (int k = 0; k < 2; ++k) dst[n][k] = *(const LAS bf16x8*)(lds + PG8_SB(b, h) + boff + n * 2048 + k * 1024); } while (0)
; #define PG8_MMA(ai, bj, At, Bt) do { __builtin_amdgcn_s_setprio(1); _Pragma("unroll") for (int m = 0; m < 4; ++m) _Pragma("unroll") for (int n = 0; n < 2; ++n) _Pragma("unroll") for (int k = 0; k < 2; ++k) \
;         acc[ai][bj][m][n] = __builtin_amdgcn_mfma_f32_16x16x32_bf16(Bt[n][k], At[m][k], acc[ai][bj][m][n], 0, 0, 0); __builtin_amdgcn_s_setprio(0); } while (0)
; #define PG8_WAIT_V(n) asm volatile("s_waitcnt vmcnt(" #n ")" ::: "memory")
; #define PG8_WAIT_L(n) asm volatile("s_waitcnt lgkmcnt(" #n ")" ::: "memory")
; #define PG8_BAR __builtin_amdgcn_s_barrier()
; #define PG8_SCHED __builtin_amdgcn_sched_barrier(0)
; template <class Epi, class Sched, int KC, bool ALIGN_EPI = false, bool SP2 = false, bool ATILED = false>
; __device__ __forceinline__ void gemm_phase(LAS unsigned char* lds, const Gemm g, const Sched& S, const Epi& E, int wave_s) {
;     ...
;             PG8_LDB(B0, 1, 0); PG8_LDB(B1, 1, 1); PG8_SCHED; PG8_LDA(At, 1, 0); PG8_STAGE(PG8_SA(0, 1), a2 + hstepA, voffA);
;             PG8_WAIT_V(8); PG8_WAIT_L(0); PG8_BAR; PG8_MMA(0, 0, At, B0); PG8_MMA(0, 1, At, B1); PG8_BAR; PG8_SCHED;
;             PG8_LDA(At, 1, 1); PG8_STAGE(PG8_SB(1, 0), b3, voffB); PG8_STAGE(PG8_SB(1, 1), b3 + hstepB, voffB); PG8_STAGE(PG8_SA(1, 0), a3, voffA);
;             PG8_WAIT_V(8); PG8_WAIT_L(0); PG8_BAR; PG8_MMA(1, 0, At, B0); PG8_MMA(1, 1, At, B1); PG8_BAR; PG8_SCHED;
	s_add_i32 s49, 0, 0x18000
	s_add_i32 s50, 0, 0x1c000
	v_add_u32_e32 v142, s49, v229
	v_add_u32_e32 v158, s50, v229
	ds_read_b128 v[130:133], v142
	ds_read_b128 v[134:137], v142 offset:1024
	ds_read_b128 v[138:141], v142 offset:2048
	ds_read_b128 v[142:145], v142 offset:3072
	ds_read_b128 v[146:149], v158
	ds_read_b128 v[150:153], v158 offset:1024
	ds_read_b128 v[154:157], v158 offset:2048
	ds_read_b128 v[158:161], v158 offset:3072
	s_add_u32 s22, s22, 0x80000
	s_addc_u32 s23, s23, 0
	s_mov_b32 m0, s36
	ds_read_b128 v[162:165], v230 offset:32768
	ds_read_b128 v[166:169], v230 offset:33792
	ds_read_b128 v[170:173], v230 offset:34816
	ds_read_b128 v[174:177], v230 offset:35840
	ds_read_b128 v[178:181], v230 offset:36864
	ds_read_b128 v[182:185], v230 offset:37888
	ds_read_b128 v[186:189], v230 offset:38912
	ds_read_b128 v[190:193], v230 offset:39936
	global_load_lds_dwordx4 v198, s[22:23]
	s_mov_b32 m0, s37
	s_nop 0
	global_load_lds_dwordx4 v200, s[22:23]
	s_waitcnt vmcnt(8)
	s_waitcnt lgkmcnt(0)
	s_barrier
	s_waitcnt lgkmcnt(0)
	v_mfma_f32_16x16x32_bf16 v[126:129], v[130:133], v[162:165], v[126:129]
	v_mfma_f32_16x16x32_bf16 v[122:125], v[138:141], v[162:165], v[122:125]
	v_mfma_f32_16x16x32_bf16 v[110:113], v[130:133], v[170:173], v[110:113]
	v_mfma_f32_16x16x32_bf16 v[106:109], v[138:141], v[170:173], v[106:109]
	v_mfma_f32_16x16x32_bf16 v[94:97], v[130:133], v[178:181], v[94:97]
	v_mfma_f32_16x16x32_bf16 v[90:93], v[138:141], v[178:181], v[90:93]
	v_mfma_f32_16x16x32_bf16 v[78:81], v[130:133], v[186:189], v[78:81]
	v_mfma_f32_16x16x32_bf16 v[74:77], v[138:141], v[186:189], v[74:77]
	v_mfma_f32_16x16x32_bf16 v[126:129], v[134:137], v[166:169], v[126:129]
	v_mfma_f32_16x16x32_bf16 v[122:125], v[142:145], v[166:169], v[122:125]
	v_mfma_f32_16x16x32_bf16 v[110:113], v[134:137], v[174:177], v[110:113]
	v_mfma_f32_16x16x32_bf16 v[106:109], v[142:145], v[174:177], v[106:109]
	v_mfma_f32_16x16x32_bf16 v[94:97], v[134:137], v[182:185], v[94:97]
	v_mfma_f32_16x16x32_bf16 v[90:93], v[142:145], v[182:185], v[90:93]
	v_mfma_f32_16x16x32_bf16 v[78:81], v[134:137], v[190:193], v[78:81]
	v_mfma_f32_16x16x32_bf16 v[74:77], v[142:145], v[190:193], v[74:77]
	v_mfma_f32_16x16x32_bf16 v[118:121], v[146:149], v[162:165], v[118:121]
	v_mfma_f32_16x16x32_bf16 v[114:117], v[154:157], v[162:165], v[114:117]
	v_mfma_f32_16x16x32_bf16 v[102:105], v[146:149], v[170:173], v[102:105]
	v_mfma_f32_16x16x32_bf16 v[98:101], v[154:157], v[170:173], v[98:101]
	v_mfma_f32_16x16x32_bf16 v[86:89], v[146:149], v[178:181], v[86:89]
	v_mfma_f32_16x16x32_bf16 v[82:85], v[154:157], v[178:181], v[82:85]
	v_mfma_f32_16x16x32_bf16 v[70:73], v[146:149], v[186:189], v[70:73]
	v_mfma_f32_16x16x32_bf16 v[66:69], v[154:157], v[186:189], v[66:69]
	v_mfma_f32_16x16x32_bf16 v[118:121], v[150:153], v[166:169], v[118:121]
	v_mfma_f32_16x16x32_bf16 v[114:117], v[158:161], v[166:169], v[114:117]
	v_mfma_f32_16x16x32_bf16 v[102:105], v[150:153], v[174:177], v[102:105]
	v_mfma_f32_16x16x32_bf16 v[98:101], v[158:161], v[174:177], v[98:101]
	v_mfma_f32_16x16x32_bf16 v[86:89], v[150:153], v[182:185], v[86:89]
	v_mfma_f32_16x16x32_bf16 v[82:85], v[158:161], v[182:185], v[82:85]
	v_mfma_f32_16x16x32_bf16 v[70:73], v[150:153], v[190:193], v[70:73]
	v_mfma_f32_16x16x32_bf16 v[66:69], v[158:161], v[190:193], v[66:69]
	s_barrier
	s_add_u32 s98, s20, 0x80
	s_addc_u32 s99, s21, 0
	s_add_i32 s22, s49, s31
	s_mov_b32 m0, s22
	ds_read_b128 v[162:165], v230 offset:49152
	ds_read_b128 v[166:169], v230 offset:50176
	ds_read_b128 v[170:173], v230 offset:51200
	ds_read_b128 v[174:177], v230 offset:52224
	ds_read_b128 v[178:181], v230 offset:53248
	ds_read_b128 v[182:185], v230 offset:54272
	ds_read_b128 v[186:189], v230 offset:55296
	ds_read_b128 v[190:193], v230 offset:56320
	global_load_lds_dwordx4 v0, s[98:99]
	s_add_i32 m0, s22, 0x2000
	s_add_u32 s20, s20, 0x20080
	s_addc_u32 s21, s21, 0
	s_add_i32 s22, s50, s31
	global_load_lds_dwordx4 v202, s[98:99]
	s_mov_b32 m0, s22
	s_nop 0
	global_load_lds_dwordx4 v0, s[20:21]
	s_add_i32 m0, s22, 0x2000
	s_nop 0
	global_load_lds_dwordx4 v202, s[20:21]
	s_mov_b32 m0, s41
	s_nop 0
	global_load_lds_dwordx4 v198, s[100:101]
	s_mov_b32 m0, s42
	s_nop 0
	global_load_lds_dwordx4 v200, s[100:101]
	s_waitcnt vmcnt(8)
	s_waitcnt lgkmcnt(0)
	s_barrier
	s_waitcnt lgkmcnt(0)
	v_mfma_f32_16x16x32_bf16 v[62:65], v[130:133], v[162:165], v[62:65]
	v_mfma_f32_16x16x32_bf16 v[58:61], v[138:141], v[162:165], v[58:61]
	v_mfma_f32_16x16x32_bf16 v[46:49], v[130:133], v[170:173], v[46:49]
	v_mfma_f32_16x16x32_bf16 v[42:45], v[138:141], v[170:173], v[42:45]
	v_mfma_f32_16x16x32_bf16 v[30:33], v[130:133], v[178:181], v[30:33]
	v_mfma_f32_16x16x32_bf16 v[26:29], v[138:141], v[178:181], v[26:29]
	v_mfma_f32_16x16x32_bf16 v[14:17], v[130:133], v[186:189], v[14:17]
	v_mfma_f32_16x16x32_bf16 v[10:13], v[138:141], v[186:189], v[10:13]
	v_mfma_f32_16x16x32_bf16 v[62:65], v[134:137], v[166:169], v[62:65]
	v_mfma_f32_16x16x32_bf16 v[58:61], v[142:145], v[166:169], v[58:61]
	v_mfma_f32_16x16x32_bf16 v[46:49], v[134:137], v[174:177], v[46:49]
	v_mfma_f32_16x16x32_bf16 v[42:45], v[142:145], v[174:177], v[42:45]
	v_mfma_f32_16x16x32_bf16 v[30:33], v[134:137], v[182:185], v[30:33]
	v_mfma_f32_16x16x32_bf16 v[26:29], v[142:145], v[182:185], v[26:29]
	v_mfma_f32_16x16x32_bf16 v[14:17], v[134:137], v[190:193], v[14:17]
	v_mfma_f32_16x16x32_bf16 v[10:13], v[142:145], v[190:193], v[10:13]
	v_mfma_f32_16x16x32_bf16 v[54:57], v[146:149], v[162:165], v[54:57]
	v_mfma_f32_16x16x32_bf16 v[50:53], v[154:157], v[162:165], v[50:53]
	v_mfma_f32_16x16x32_bf16 v[38:41], v[146:149], v[170:173], v[38:41]
	v_mfma_f32_16x16x32_bf16 v[34:37], v[154:157], v[170:173], v[34:37]
	v_mfma_f32_16x16x32_bf16 v[22:25], v[146:149], v[178:181], v[22:25]
	v_mfma_f32_16x16x32_bf16 v[18:21], v[154:157], v[178:181], v[18:21]
	v_mfma_f32_16x16x32_bf16 v[6:9], v[146:149], v[186:189], v[6:9]
	v_mfma_f32_16x16x32_bf16 v[2:5], v[154:157], v[186:189], v[2:5]
	v_mfma_f32_16x16x32_bf16 v[54:57], v[150:153], v[166:169], v[54:57]
	v_mfma_f32_16x16x32_bf16 v[50:53], v[158:161], v[166:169], v[50:53]
	v_mfma_f32_16x16x32_bf16 v[38:41], v[150:153], v[174:177], v[38:41]
	v_mfma_f32_16x16x32_bf16 v[34:37], v[158:161], v[174:177], v[34:37]
	v_mfma_f32_16x16x32_bf16 v[22:25], v[150:153], v[182:185], v[22:25]
	v_mfma_f32_16x16x32_bf16 v[18:21], v[158:161], v[182:185], v[18:21]
	v_mfma_f32_16x16x32_bf16 v[6:9], v[150:153], v[190:193], v[6:9]
	v_mfma_f32_16x16x32_bf16 v[2:5], v[158:161], v[190:193], v[2:5]
	s_barrier
; #define GAS __attribute__((address_space(1)))
; DI unsigned cvtpk(float lo, float hi) { unsigned r; asm volatile("v_cvt_pk_bf16_f32 %0, %1, %2" : "=v"(r) : "v"(lo), "v"(hi)); return r; }
;     DI void operator()(const f32x4 (&acc)[2][2][4][2], const Unit& u, int wr, int wc, int fr, int fq) const {
;         const int row0 = u.pm * BM + wr * 64 + fr, col0 = u.pn * BM + wc * 64 + 8 * fq;
;         const size_t hbase = (size_t)u.pn * ((size_t)M * 256) + wc * 64 + 8 * fq;
;         u32x4 H[2][4][2];
; #pragma unroll
;         for (int ai = 0; ai < 2; ++ai)
; #pragma unroll
;             for (int m = 0; m < 4; ++m)
; #pragma unroll
;                 for (int bj = 0; bj < 2; ++bj) H[ai][m][bj] = *(const GAS u32x4*)(hi + hbase + (size_t)(row0 + ai * HALF + m * 16) * 256 + bj * 32);
;         asm volatile("" ::: "memory");
; #pragma unroll
;         for (int ai = 0; ai < 2; ++ai) {
; #pragma unroll
;             for (int m = 0; m < 4; ++m) {
;                 const int r = row0 + ai * HALF + m * 16; const size_t off = (size_t)r * DM + col0; float ss = 0.f;
; #pragma unroll
;                 for (int bj = 0; bj < 2; ++bj) {
;                     const u32x4 h = H[ai][m][bj];
;                     const f32x4 a0 = acc[ai][bj][m][0], a1 = acc[ai][bj][m][1];
;                     float v[8];
;                     v[0] = bflo(h.x) + a0[0] * scale; v[1] = bfhi(h.x) + a0[1] * scale;
;                     v[2] = bflo(h.y) + a0[2] * scale; v[3] = bfhi(h.y) + a0[3] * scale;
;                     v[4] = bflo(h.z) + a1[0] * scale; v[5] = bfhi(h.z) + a1[1] * scale;
;                     v[6] = bflo(h.w) + a1[2] * scale; v[7] = bfhi(h.w) + a1[3] * scale;
; #pragma unroll
;                     for (int e = 0; e < 8; ++e) ss += v[e] * v[e];
;                     u32x4 nh;
;                     nh.x = cvtpk(v[0], v[1]); nh.y = cvtpk(v[2], v[3]); nh.z = cvtpk(v[4], v[5]); nh.w = cvtpk(v[6], v[7]);
;                     *(GAS u32x4*)(hi + hbase + (size_t)r * 256 + bj * 32) = nh;
;                     if (out) { *(GAS f32x4*)(out + off + bj * 32) = (f32x4){v[0], v[1], v[2], v[3]}; *(GAS f32x4*)(out + off + bj * 32 + 4) = (f32x4){v[4], v[5], v[6], v[7]}; }
;                 }
;                 ss = sum_xor32(sum_xor16(ss));
;                 if (fq == 0) ((GAS float*)rowss)[(size_t)(u.pn * 4 + wc) * M + r] = ss;
	s_add_i32 s48, s48, 2
	s_add_u32 s46, s46, 0x100
	s_addc_u32 s47, s47, 0
	s_add_u32 s18, s18, 0x100
	s_addc_u32 s19, s19, 0
	s_cmp_gt_u32 s48, 29
	s_cbranch_scc0 .LBB0_1021
	v_lshl_add_u32 v210, s16, 8, v228
	s_ashr_i32 s15, s14, 31
	s_lshl_b64 s[16:17], s[14:15], 23
	v_ashrrev_i32_e32 v211, 31, v210
	v_lshl_add_u64 v[130:131], v[204:205], 0, s[16:17]
	v_lshlrev_b64 v[132:133], 9, v[210:211]
	v_lshl_add_u64 v[226:227], v[130:131], 0, v[132:133]
	global_load_dwordx4 v[190:193], v[226:227], off
	global_load_dwordx4 v[186:189], v[226:227], off offset:64
	v_or_b32_e32 v132, 16, v210
	v_ashrrev_i32_e32 v133, 31, v132
	v_lshlrev_b64 v[132:133], 9, v[132:133]
	v_lshl_add_u64 v[224:225], v[130:131], 0, v[132:133]
	v_or_b32_e32 v132, 32, v210
	v_ashrrev_i32_e32 v133, 31, v132
	v_lshlrev_b64 v[132:133], 9, v[132:133]
	v_lshl_add_u64 v[222:223], v[130:131], 0, v[132:133]
	v_or_b32_e32 v132, 48, v210
	v_ashrrev_i32_e32 v133, 31, v132
	v_lshlrev_b64 v[132:133], 9, v[132:133]
	s_mov_b32 s3, 0x10000
	v_lshl_add_u64 v[220:221], v[130:131], 0, v[132:133]
	v_add_co_u32_e32 v130, vcc, s3, v226
	s_mov_b64 s[16:17], 0x10000
	s_nop 0
	v_addc_co_u32_e32 v131, vcc, 0, v227, vcc
	s_mov_b32 s3, 0x12000
	global_load_dwordx4 v[182:185], v[224:225], off
	global_load_dwordx4 v[178:181], v[224:225], off offset:64
	global_load_dwordx4 v[174:177], v[222:223], off
	global_load_dwordx4 v[170:173], v[222:223], off offset:64
	global_load_dwordx4 v[166:169], v[220:221], off
	global_load_dwordx4 v[162:165], v[220:221], off offset:64
	v_lshl_add_u64 v[218:219], v[226:227], 0, s[16:17]
	global_load_dwordx4 v[158:161], v[130:131], off
	global_load_dwordx4 v[150:153], v[218:219], off offset:64
	v_add_co_u32_e32 v130, vcc, s3, v226
	s_mov_b64 s[16:17], 0x12000
	s_nop 0
	v_addc_co_u32_e32 v131, vcc, 0, v227, vcc
	s_mov_b32 s3, 0x14000
	v_lshl_add_u64 v[216:217], v[226:227], 0, s[16:17]
	global_load_dwordx4 v[154:157], v[130:131], off
	global_load_dwordx4 v[146:149], v[216:217], off offset:64
	v_add_co_u32_e32 v130, vcc, s3, v226
	s_mov_b64 s[16:17], 0x14000
	s_nop 0
	v_addc_co_u32_e32 v131, vcc, 0, v227, vcc
	s_mov_b32 s3, 0x16000
	v_lshl_add_u64 v[214:215], v[226:227], 0, s[16:17]
	global_load_dwordx4 v[142:145], v[130:131], off
	global_load_dwordx4 v[134:137], v[214:215], off offset:64
	v_add_co_u32_e32 v130, vcc, s3, v226
	s_mov_b64 s[16:17], 0x16000
	s_nop 0
	v_addc_co_u32_e32 v131, vcc, 0, v227, vcc
	v_lshl_add_u64 v[212:213], v[226:227], 0, s[16:17]
	global_load_dwordx4 v[138:141], v[130:131], off
	s_nop 0
	global_load_dwordx4 v[130:133], v[212:213], off offset:64
	s_lshl_b32 s3, s14, 2
	s_or_b32 s14, s3, s40
	s_ashr_i32 s15, s14, 31
	s_lshl_b64 s[14:15], s[14:15], 16
	s_waitcnt vmcnt(0)
	v_lshlrev_b32_e32 v194, 16, v190
	v_and_b32_e32 v190, 0xffff0000, v190
	v_add_f32_e32 v127, v127, v190
	v_lshlrev_b32_e32 v190, 16, v191
	v_add_f32_e32 v128, v128, v190
	v_and_b32_e32 v190, 0xffff0000, v191
	v_add_f32_e32 v129, v129, v190
	v_lshlrev_b32_e32 v190, 16, v192
	v_add_f32_e32 v190, v122, v190
	v_and_b32_e32 v122, 0xffff0000, v192
	v_add_f32_e32 v191, v123, v122
	v_lshlrev_b32_e32 v122, 16, v193
	v_add_f32_e32 v126, v126, v194
	v_add_f32_e32 v192, v124, v122
	v_and_b32_e32 v122, 0xffff0000, v193
	v_mul_f32_e32 v193, v127, v127
	v_fmac_f32_e32 v193, v126, v126
	v_fmac_f32_e32 v193, v128, v128
	v_fmac_f32_e32 v193, v129, v129
	v_fmac_f32_e32 v193, v190, v190
	v_fmac_f32_e32 v193, v191, v191
	v_add_f32_e32 v125, v125, v122
	v_fmac_f32_e32 v193, v192, v192
	v_cvt_pk_bf16_f32 v122, v126, v127
	v_fmac_f32_e32 v193, v125, v125
	v_cvt_pk_bf16_f32 v123, v128, v129
	v_cvt_pk_bf16_f32 v124, v190, v191
	v_cvt_pk_bf16_f32 v125, v192, v125
	global_store_dwordx4 v[226:227], v[122:125], off nt
	s_nop 1
	v_lshlrev_b32_e32 v122, 16, v186
	v_add_f32_e32 v118, v118, v122
	v_and_b32_e32 v122, 0xffff0000, v186
	v_add_f32_e32 v119, v119, v122
	v_lshlrev_b32_e32 v122, 16, v187
	v_fmac_f32_e32 v193, v118, v118
	v_add_f32_e32 v120, v120, v122
	v_and_b32_e32 v122, 0xffff0000, v187
	v_fmac_f32_e32 v193, v119, v119
	v_add_f32_e32 v121, v121, v122
	v_lshlrev_b32_e32 v122, 16, v188
	v_fmac_f32_e32 v193, v120, v120
	v_add_f32_e32 v122, v114, v122
	v_and_b32_e32 v114, 0xffff0000, v188
	v_fmac_f32_e32 v193, v121, v121
	v_add_f32_e32 v123, v115, v114
	v_lshlrev_b32_e32 v114, 16, v189
	v_fmac_f32_e32 v193, v122, v122
	v_add_f32_e32 v124, v116, v114
	v_and_b32_e32 v114, 0xffff0000, v189
	v_fmac_f32_e32 v193, v123, v123
	v_add_f32_e32 v117, v117, v114
	v_fmac_f32_e32 v193, v124, v124
	v_fmac_f32_e32 v193, v117, v117
	v_cvt_pk_bf16_f32 v114, v118, v119
	v_cvt_pk_bf16_f32 v115, v120, v121
	v_cvt_pk_bf16_f32 v116, v122, v123
	v_cvt_pk_bf16_f32 v117, v124, v117
	global_store_dwordx4 v[226:227], v[114:117], off offset:64 nt
	s_nop 1
	v_mov_b32_e32 v114, v193
	s_nop 1
	v_permlane16_swap_b32_e32 v193, v114
	v_add_f32_e32 v114, v193, v114
	v_mov_b32_e32 v115, v114
	s_nop 1
	v_permlane32_swap_b32_e32 v114, v115
	s_and_saveexec_b64 s[16:17], s[4:5]
	s_cbranch_execz .LBB0_1024
	s_add_u32 s18, s38, s14
	s_addc_u32 s19, s39, s15
	v_lshl_add_u64 v[116:117], v[210:211], 2, s[18:19]
	v_add_f32_e32 v114, v114, v115
	global_store_dword v[116:117], v114, off
; #define GAS __attribute__((address_space(1)))
; DI unsigned cvtpk(float lo, float hi) { unsigned r; asm volatile("v_cvt_pk_bf16_f32 %0, %1, %2" : "=v"(r) : "v"(lo), "v"(hi)); return r; }
; DI float sum_xor16(float s) { auto r = __builtin_amdgcn_permlane16_swap(__float_as_uint(s), __float_as_uint(s), false, false); return __uint_as_float(r[0]) + __uint_as_float(r[1]); }
; DI float sum_xor32(float s) { auto r = __builtin_amdgcn_permlane32_swap(__float_as_uint(s), __float_as_uint(s), false, false); return __uint_as_float(r[0]) + __uint_as_float(r[1]); }
;     DI void operator()(const f32x4 (&acc)[2][2][4][2], const Unit& u, int wr, int wc, int fr, int fq) const {
;     ...
;             for (int m = 0; m < 4; ++m) {
;                 const int r = row0 + ai * HALF + m * 16; const size_t off = (size_t)r * DM + col0; float ss = 0.f;
; #pragma unroll
;                 for (int bj = 0; bj < 2; ++bj) {
;                     const u32x4 h = H[ai][m][bj];
;                     const f32x4 a0 = acc[ai][bj][m][0], a1 = acc[ai][bj][m][1];
;                     float v[8];
;                     v[0] = bflo(h.x) + a0[0] * scale; v[1] = bfhi(h.x) + a0[1] * scale;
;                     v[2] = bflo(h.y) + a0[2] * scale; v[3] = bfhi(h.y) + a0[3] * scale;
;                     v[4] = bflo(h.z) + a1[0] * scale; v[5] = bfhi(h.z) + a1[1] * scale;
;                     v[6] = bflo(h.w) + a1[2] * scale; v[7] = bfhi(h.w) + a1[3] * scale;
; #pragma unroll
;                     for (int e = 0; e < 8; ++e) ss += v[e] * v[e];
;                     u32x4 nh;
;                     nh.x = cvtpk(v[0], v[1]); nh.y = cvtpk(v[2], v[3]); nh.z = cvtpk(v[4], v[5]); nh.w = cvtpk(v[6], v[7]);
;                     *(GAS u32x4*)(hi + hbase + (size_t)r * 256 + bj * 32) = nh;
;                     if (out) { *(GAS f32x4*)(out + off + bj * 32) = (f32x4){v[0], v[1], v[2], v[3]}; *(GAS f32x4*)(out + off + bj * 32 + 4) = (f32x4){v[4], v[5], v[6], v[7]}; }
;                 }
;                 ss = sum_xor32(sum_xor16(ss));
;                 if (fq == 0) ((GAS float*)rowss)[(size_t)(u.pn * 4 + wc) * M + r] = ss;
.LBB0_1024:
	s_or_b64 exec, exec, s[16:17]
	v_lshlrev_b32_e32 v114, 16, v182
	v_add_f32_e32 v110, v110, v114
	v_and_b32_e32 v114, 0xffff0000, v182
	v_add_f32_e32 v111, v111, v114
	v_lshlrev_b32_e32 v114, 16, v183
	v_mul_f32_e32 v117, v111, v111
	v_add_f32_e32 v112, v112, v114
	v_and_b32_e32 v114, 0xffff0000, v183
	v_fmac_f32_e32 v117, v110, v110
	v_add_f32_e32 v113, v113, v114
	v_lshlrev_b32_e32 v114, 16, v184
	v_fmac_f32_e32 v117, v112, v112
	v_add_f32_e32 v114, v106, v114
	v_and_b32_e32 v106, 0xffff0000, v184
	v_fmac_f32_e32 v117, v113, v113
	v_add_f32_e32 v115, v107, v106
	v_lshlrev_b32_e32 v106, 16, v185
	v_fmac_f32_e32 v117, v114, v114
	v_add_f32_e32 v116, v108, v106
	v_and_b32_e32 v106, 0xffff0000, v185
	v_fmac_f32_e32 v117, v115, v115
	v_add_f32_e32 v109, v109, v106
	v_fmac_f32_e32 v117, v116, v116
	v_cvt_pk_bf16_f32 v106, v110, v111
	v_fmac_f32_e32 v117, v109, v109
	v_cvt_pk_bf16_f32 v107, v112, v113
	v_cvt_pk_bf16_f32 v108, v114, v115
	v_cvt_pk_bf16_f32 v109, v116, v109
	global_store_dwordx4 v[224:225], v[106:109], off nt
	s_nop 1
	v_lshlrev_b32_e32 v106, 16, v178
	v_add_f32_e32 v102, v102, v106
	v_and_b32_e32 v106, 0xffff0000, v178
	v_add_f32_e32 v103, v103, v106
	v_lshlrev_b32_e32 v106, 16, v179
	v_fmac_f32_e32 v117, v102, v102
	v_add_f32_e32 v104, v104, v106
	v_and_b32_e32 v106, 0xffff0000, v179
	v_fmac_f32_e32 v117, v103, v103
	v_add_f32_e32 v105, v105, v106
	v_lshlrev_b32_e32 v106, 16, v180
	v_fmac_f32_e32 v117, v104, v104
	v_add_f32_e32 v106, v98, v106
	v_and_b32_e32 v98, 0xffff0000, v180
	v_fmac_f32_e32 v117, v105, v105
	v_add_f32_e32 v107, v99, v98
	v_lshlrev_b32_e32 v98, 16, v181
	v_fmac_f32_e32 v117, v106, v106
	v_add_f32_e32 v108, v100, v98
	v_and_b32_e32 v98, 0xffff0000, v181
	v_fmac_f32_e32 v117, v107, v107
	v_add_f32_e32 v101, v101, v98
	v_fmac_f32_e32 v117, v108, v108
	v_fmac_f32_e32 v117, v101, v101
	v_cvt_pk_bf16_f32 v98, v102, v103
	v_cvt_pk_bf16_f32 v99, v104, v105
	v_cvt_pk_bf16_f32 v100, v106, v107
	v_cvt_pk_bf16_f32 v101, v108, v101
	global_store_dwordx4 v[224:225], v[98:101], off offset:64 nt
	s_nop 1
	v_mov_b32_e32 v98, v117
	s_nop 1
	v_permlane16_swap_b32_e32 v117, v98
	v_add_f32_e32 v98, v117, v98
	v_mov_b32_e32 v99, v98
	s_nop 1
	v_permlane32_swap_b32_e32 v98, v99
	s_and_saveexec_b64 s[16:17], s[4:5]
	s_cbranch_execz .LBB0_1026
	s_add_u32 s18, s38, s14
	s_addc_u32 s19, s39, s15
	v_lshl_add_u64 v[100:101], v[210:211], 2, s[18:19]
	v_add_f32_e32 v98, v98, v99
	global_store_dword v[100:101], v98, off offset:64
.LBB0_1026:
	s_or_b64 exec, exec, s[16:17]
	v_lshlrev_b32_e32 v98, 16, v174
	v_add_f32_e32 v94, v94, v98
	v_and_b32_e32 v98, 0xffff0000, v174
	v_add_f32_e32 v95, v95, v98
	v_lshlrev_b32_e32 v98, 16, v175
	v_mul_f32_e32 v101, v95, v95
	v_add_f32_e32 v96, v96, v98
	v_and_b32_e32 v98, 0xffff0000, v175
	v_fmac_f32_e32 v101, v94, v94
	v_add_f32_e32 v97, v97, v98
	v_lshlrev_b32_e32 v98, 16, v176
	v_fmac_f32_e32 v101, v96, v96
	v_add_f32_e32 v98, v90, v98
	v_and_b32_e32 v90, 0xffff0000, v176
	v_fmac_f32_e32 v101, v97, v97
	v_add_f32_e32 v99, v91, v90
	v_lshlrev_b32_e32 v90, 16, v177
	v_fmac_f32_e32 v101, v98, v98
	v_add_f32_e32 v100, v92, v90
	v_and_b32_e32 v90, 0xffff0000, v177
	v_fmac_f32_e32 v101, v99, v99
	v_add_f32_e32 v93, v93, v90
	v_fmac_f32_e32 v101, v100, v100
	v_cvt_pk_bf16_f32 v90, v94, v95
	v_fmac_f32_e32 v101, v93, v93
	v_cvt_pk_bf16_f32 v91, v96, v97
	v_cvt_pk_bf16_f32 v92, v98, v99
	v_cvt_pk_bf16_f32 v93, v100, v93
	global_store_dwordx4 v[222:223], v[90:93], off nt
	s_nop 1
	v_lshlrev_b32_e32 v90, 16, v170
	v_add_f32_e32 v86, v86, v90
	v_and_b32_e32 v90, 0xffff0000, v170
	v_add_f32_e32 v87, v87, v90
	v_lshlrev_b32_e32 v90, 16, v171
	v_fmac_f32_e32 v101, v86, v86
	v_add_f32_e32 v88, v88, v90
	v_and_b32_e32 v90, 0xffff0000, v171
	v_fmac_f32_e32 v101, v87, v87
	v_add_f32_e32 v89, v89, v90
	v_lshlrev_b32_e32 v90, 16, v172
	v_fmac_f32_e32 v101, v88, v88
	v_add_f32_e32 v90, v82, v90
	v_and_b32_e32 v82, 0xffff0000, v172
	v_fmac_f32_e32 v101, v89, v89
	v_add_f32_e32 v91, v83, v82
	v_lshlrev_b32_e32 v82, 16, v173
	v_fmac_f32_e32 v101, v90, v90
	v_add_f32_e32 v92, v84, v82
	v_and_b32_e32 v82, 0xffff0000, v173
	v_fmac_f32_e32 v101, v91, v91
	v_add_f32_e32 v85, v85, v82
	v_fmac_f32_e32 v101, v92, v92
	v_fmac_f32_e32 v101, v85, v85
	v_cvt_pk_bf16_f32 v82, v86, v87
	v_cvt_pk_bf16_f32 v83, v88, v89
	v_cvt_pk_bf16_f32 v84, v90, v91
	v_cvt_pk_bf16_f32 v85, v92, v85
	global_store_dwordx4 v[222:223], v[82:85], off offset:64 nt
	s_nop 1
	v_mov_b32_e32 v82, v101
	s_nop 1
	v_permlane16_swap_b32_e32 v101, v82
	v_add_f32_e32 v82, v101, v82
	v_mov_b32_e32 v83, v82
	s_nop 1
	v_permlane32_swap_b32_e32 v82, v83
	s_and_saveexec_b64 s[16:17], s[4:5]
	s_cbranch_execz .LBB0_1028
	s_add_u32 s18, s38, s14
	s_addc_u32 s19, s39, s15
	v_lshl_add_u64 v[84:85], v[210:211], 2, s[18:19]
	v_add_f32_e32 v82, v82, v83
	global_store_dword v[84:85], v82, off offset:128
; #define GAS __attribute__((address_space(1)))
; DI unsigned cvtpk(float lo, float hi) { unsigned r; asm volatile("v_cvt_pk_bf16_f32 %0, %1, %2" : "=v"(r) : "v"(lo), "v"(hi)); return r; }
; DI float sum_xor16(float s) { auto r = __builtin_amdgcn_permlane16_swap(__float_as_uint(s), __float_as_uint(s), false, false); return __uint_as_float(r[0]) + __uint_as_float(r[1]); }
; DI float sum_xor32(float s) { auto r = __builtin_amdgcn_permlane32_swap(__float_as_uint(s), __float_as_uint(s), false, false); return __uint_as_float(r[0]) + __uint_as_float(r[1]); }
;     DI void operator()(const f32x4 (&acc)[2][2][4][2], const Unit& u, int wr, int wc, int fr, int fq) const {
;     ...
;             for (int m = 0; m < 4; ++m) {
;                 const int r = row0 + ai * HALF + m * 16; const size_t off = (size_t)r * DM + col0; float ss = 0.f;
; #pragma unroll
;                 for (int bj = 0; bj < 2; ++bj) {
;                     const u32x4 h = H[ai][m][bj];
;                     const f32x4 a0 = acc[ai][bj][m][0], a1 = acc[ai][bj][m][1];
;                     float v[8];
;                     v[0] = bflo(h.x) + a0[0] * scale; v[1] = bfhi(h.x) + a0[1] * scale;
;                     v[2] = bflo(h.y) + a0[2] * scale; v[3] = bfhi(h.y) + a0[3] * scale;
;                     v[4] = bflo(h.z) + a1[0] * scale; v[5] = bfhi(h.z) + a1[1] * scale;
;                     v[6] = bflo(h.w) + a1[2] * scale; v[7] = bfhi(h.w) + a1[3] * scale;
; #pragma unroll
;                     for (int e = 0; e < 8; ++e) ss += v[e] * v[e];
;                     u32x4 nh;
;                     nh.x = cvtpk(v[0], v[1]); nh.y = cvtpk(v[2], v[3]); nh.z = cvtpk(v[4], v[5]); nh.w = cvtpk(v[6], v[7]);
;                     *(GAS u32x4*)(hi + hbase + (size_t)r * 256 + bj * 32) = nh;
;                     if (out) { *(GAS f32x4*)(out + off + bj * 32) = (f32x4){v[0], v[1], v[2], v[3]}; *(GAS f32x4*)(out + off + bj * 32 + 4) = (f32x4){v[4], v[5], v[6], v[7]}; }
;                 }
;                 ss = sum_xor32(sum_xor16(ss));
;                 if (fq == 0) ((GAS float*)rowss)[(size_t)(u.pn * 4 + wc) * M + r] = ss;
.LBB0_1028:
	s_or_b64 exec, exec, s[16:17]
	v_lshlrev_b32_e32 v82, 16, v166
	v_add_f32_e32 v78, v78, v82
	v_and_b32_e32 v82, 0xffff0000, v166
	v_add_f32_e32 v79, v79, v82
	v_lshlrev_b32_e32 v82, 16, v167
	v_mul_f32_e32 v85, v79, v79
	v_add_f32_e32 v80, v80, v82
	v_and_b32_e32 v82, 0xffff0000, v167
	v_fmac_f32_e32 v85, v78, v78
	v_add_f32_e32 v81, v81, v82
	v_lshlrev_b32_e32 v82, 16, v168
	v_fmac_f32_e32 v85, v80, v80
	v_add_f32_e32 v82, v74, v82
	v_and_b32_e32 v74, 0xffff0000, v168
	v_fmac_f32_e32 v85, v81, v81
	v_add_f32_e32 v83, v75, v74
	v_lshlrev_b32_e32 v74, 16, v169
	v_fmac_f32_e32 v85, v82, v82
	v_add_f32_e32 v84, v76, v74
	v_and_b32_e32 v74, 0xffff0000, v169
	v_fmac_f32_e32 v85, v83, v83
	v_add_f32_e32 v77, v77, v74
	v_fmac_f32_e32 v85, v84, v84
	v_cvt_pk_bf16_f32 v74, v78, v79
	v_fmac_f32_e32 v85, v77, v77
	v_cvt_pk_bf16_f32 v75, v80, v81
	v_cvt_pk_bf16_f32 v76, v82, v83
	v_cvt_pk_bf16_f32 v77, v84, v77
	global_store_dwordx4 v[220:221], v[74:77], off nt
	s_nop 1
	v_lshlrev_b32_e32 v74, 16, v162
	v_add_f32_e32 v70, v70, v74
	v_and_b32_e32 v74, 0xffff0000, v162
	v_add_f32_e32 v71, v71, v74
	v_lshlrev_b32_e32 v74, 16, v163
	v_fmac_f32_e32 v85, v70, v70
	v_add_f32_e32 v72, v72, v74
	v_and_b32_e32 v74, 0xffff0000, v163
	v_fmac_f32_e32 v85, v71, v71
	v_add_f32_e32 v73, v73, v74
	v_lshlrev_b32_e32 v74, 16, v164
	v_fmac_f32_e32 v85, v72, v72
	v_add_f32_e32 v74, v66, v74
	v_and_b32_e32 v66, 0xffff0000, v164
	v_fmac_f32_e32 v85, v73, v73
	v_add_f32_e32 v75, v67, v66
	v_lshlrev_b32_e32 v66, 16, v165
	v_fmac_f32_e32 v85, v74, v74
	v_add_f32_e32 v76, v68, v66
	v_and_b32_e32 v66, 0xffff0000, v165
	v_fmac_f32_e32 v85, v75, v75
	v_add_f32_e32 v69, v69, v66
	v_fmac_f32_e32 v85, v76, v76
	v_fmac_f32_e32 v85, v69, v69
	v_cvt_pk_bf16_f32 v66, v70, v71
	v_cvt_pk_bf16_f32 v67, v72, v73
	v_cvt_pk_bf16_f32 v68, v74, v75
	v_cvt_pk_bf16_f32 v69, v76, v69
	global_store_dwordx4 v[220:221], v[66:69], off offset:64 nt
	s_nop 1
	v_mov_b32_e32 v66, v85
	s_nop 1
	v_permlane16_swap_b32_e32 v85, v66
	v_add_f32_e32 v66, v85, v66
	v_mov_b32_e32 v67, v66
	s_nop 1
	v_permlane32_swap_b32_e32 v66, v67
	s_and_saveexec_b64 s[16:17], s[4:5]
	s_cbranch_execz .LBB0_1030
	s_add_u32 s18, s38, s14
	s_addc_u32 s19, s39, s15
	v_lshl_add_u64 v[68:69], v[210:211], 2, s[18:19]
	v_add_f32_e32 v66, v66, v67
	global_store_dword v[68:69], v66, off offset:192
.LBB0_1030:
	s_or_b64 exec, exec, s[16:17]
	v_lshlrev_b32_e32 v66, 16, v158
	v_add_f32_e32 v62, v62, v66
	v_and_b32_e32 v66, 0xffff0000, v158
	v_add_f32_e32 v63, v63, v66
	v_lshlrev_b32_e32 v66, 16, v159
	v_mul_f32_e32 v69, v63, v63
	v_add_f32_e32 v64, v64, v66
	v_and_b32_e32 v66, 0xffff0000, v159
	v_fmac_f32_e32 v69, v62, v62
	v_add_f32_e32 v65, v65, v66
	v_lshlrev_b32_e32 v66, 16, v160
	v_fmac_f32_e32 v69, v64, v64
	v_add_f32_e32 v66, v58, v66
	v_and_b32_e32 v58, 0xffff0000, v160
	v_fmac_f32_e32 v69, v65, v65
	v_add_f32_e32 v67, v59, v58
	v_lshlrev_b32_e32 v58, 16, v161
	v_fmac_f32_e32 v69, v66, v66
	v_add_f32_e32 v68, v60, v58
	v_and_b32_e32 v58, 0xffff0000, v161
	v_fmac_f32_e32 v69, v67, v67
	v_add_f32_e32 v61, v61, v58
	v_fmac_f32_e32 v69, v68, v68
	v_cvt_pk_bf16_f32 v58, v62, v63
	v_fmac_f32_e32 v69, v61, v61
	v_cvt_pk_bf16_f32 v59, v64, v65
	v_cvt_pk_bf16_f32 v60, v66, v67
	v_cvt_pk_bf16_f32 v61, v68, v61
	global_store_dwordx4 v[218:219], v[58:61], off nt
	s_nop 1
	v_lshlrev_b32_e32 v58, 16, v150
	v_add_f32_e32 v54, v54, v58
	v_and_b32_e32 v58, 0xffff0000, v150
	v_add_f32_e32 v55, v55, v58
	v_lshlrev_b32_e32 v58, 16, v151
	v_fmac_f32_e32 v69, v54, v54
	v_add_f32_e32 v56, v56, v58
	v_and_b32_e32 v58, 0xffff0000, v151
	v_fmac_f32_e32 v69, v55, v55
	v_add_f32_e32 v57, v57, v58
	v_lshlrev_b32_e32 v58, 16, v152
	v_fmac_f32_e32 v69, v56, v56
	v_add_f32_e32 v58, v50, v58
	v_and_b32_e32 v50, 0xffff0000, v152
	v_fmac_f32_e32 v69, v57, v57
	v_add_f32_e32 v59, v51, v50
	v_lshlrev_b32_e32 v50, 16, v153
	v_fmac_f32_e32 v69, v58, v58
	v_add_f32_e32 v60, v52, v50
	v_and_b32_e32 v50, 0xffff0000, v153
	v_fmac_f32_e32 v69, v59, v59
	v_add_f32_e32 v53, v53, v50
	v_fmac_f32_e32 v69, v60, v60
	v_fmac_f32_e32 v69, v53, v53
	v_cvt_pk_bf16_f32 v50, v54, v55
	v_cvt_pk_bf16_f32 v51, v56, v57
	v_cvt_pk_bf16_f32 v52, v58, v59
	v_cvt_pk_bf16_f32 v53, v60, v53
	global_store_dwordx4 v[218:219], v[50:53], off offset:64 nt
	s_nop 1
	v_mov_b32_e32 v50, v69
	s_nop 1
	v_permlane16_swap_b32_e32 v69, v50
	v_add_f32_e32 v50, v69, v50
	v_mov_b32_e32 v51, v50
	s_nop 1
	v_permlane32_swap_b32_e32 v50, v51
	s_and_saveexec_b64 s[16:17], s[4:5]
	s_cbranch_execz .LBB0_1032
	s_add_u32 s18, s38, s14
	s_addc_u32 s19, s39, s15
	v_lshl_add_u64 v[52:53], v[210:211], 2, s[18:19]
	v_add_f32_e32 v50, v50, v51
	global_store_dword v[52:53], v50, off offset:512
; #define GAS __attribute__((address_space(1)))
; DI unsigned cvtpk(float lo, float hi) { unsigned r; asm volatile("v_cvt_pk_bf16_f32 %0, %1, %2" : "=v"(r) : "v"(lo), "v"(hi)); return r; }
; DI float sum_xor16(float s) { auto r = __builtin_amdgcn_permlane16_swap(__float_as_uint(s), __float_as_uint(s), false, false); return __uint_as_float(r[0]) + __uint_as_float(r[1]); }
; DI float sum_xor32(float s) { auto r = __builtin_amdgcn_permlane32_swap(__float_as_uint(s), __float_as_uint(s), false, false); return __uint_as_float(r[0]) + __uint_as_float(r[1]); }
;     DI void operator()(const f32x4 (&acc)[2][2][4][2], const Unit& u, int wr, int wc, int fr, int fq) const {
;     ...
;             for (int m = 0; m < 4; ++m) {
;                 const int r = row0 + ai * HALF + m * 16; const size_t off = (size_t)r * DM + col0; float ss = 0.f;
; #pragma unroll
;                 for (int bj = 0; bj < 2; ++bj) {
;                     const u32x4 h = H[ai][m][bj];
;                     const f32x4 a0 = acc[ai][bj][m][0], a1 = acc[ai][bj][m][1];
;                     float v[8];
;                     v[0] = bflo(h.x) + a0[0] * scale; v[1] = bfhi(h.x) + a0[1] * scale;
;                     v[2] = bflo(h.y) + a0[2] * scale; v[3] = bfhi(h.y) + a0[3] * scale;
;                     v[4] = bflo(h.z) + a1[0] * scale; v[5] = bfhi(h.z) + a1[1] * scale;
;                     v[6] = bflo(h.w) + a1[2] * scale; v[7] = bfhi(h.w) + a1[3] * scale;
; #pragma unroll
;                     for (int e = 0; e < 8; ++e) ss += v[e] * v[e];
;                     u32x4 nh;
;                     nh.x = cvtpk(v[0], v[1]); nh.y = cvtpk(v[2], v[3]); nh.z = cvtpk(v[4], v[5]); nh.w = cvtpk(v[6], v[7]);
;                     *(GAS u32x4*)(hi + hbase + (size_t)r * 256 + bj * 32) = nh;
;                     if (out) { *(GAS f32x4*)(out + off + bj * 32) = (f32x4){v[0], v[1], v[2], v[3]}; *(GAS f32x4*)(out + off + bj * 32 + 4) = (f32x4){v[4], v[5], v[6], v[7]}; }
;                 }
;                 ss = sum_xor32(sum_xor16(ss));
;                 if (fq == 0) ((GAS float*)rowss)[(size_t)(u.pn * 4 + wc) * M + r] = ss;
.LBB0_1032:
	s_or_b64 exec, exec, s[16:17]
	v_lshlrev_b32_e32 v50, 16, v154
	v_add_f32_e32 v46, v46, v50
	v_and_b32_e32 v50, 0xffff0000, v154
	v_add_f32_e32 v47, v47, v50
	v_lshlrev_b32_e32 v50, 16, v155
	v_mul_f32_e32 v53, v47, v47
	v_add_f32_e32 v48, v48, v50
	v_and_b32_e32 v50, 0xffff0000, v155
	v_fmac_f32_e32 v53, v46, v46
	v_add_f32_e32 v49, v49, v50
	v_lshlrev_b32_e32 v50, 16, v156
	v_fmac_f32_e32 v53, v48, v48
	v_add_f32_e32 v50, v42, v50
	v_and_b32_e32 v42, 0xffff0000, v156
	v_fmac_f32_e32 v53, v49, v49
	v_add_f32_e32 v51, v43, v42
	v_lshlrev_b32_e32 v42, 16, v157
	v_fmac_f32_e32 v53, v50, v50
	v_add_f32_e32 v52, v44, v42
	v_and_b32_e32 v42, 0xffff0000, v157
	v_fmac_f32_e32 v53, v51, v51
	v_add_f32_e32 v45, v45, v42
	v_fmac_f32_e32 v53, v52, v52
	v_cvt_pk_bf16_f32 v42, v46, v47
	v_fmac_f32_e32 v53, v45, v45
	v_cvt_pk_bf16_f32 v43, v48, v49
	v_cvt_pk_bf16_f32 v44, v50, v51
	v_cvt_pk_bf16_f32 v45, v52, v45
	global_store_dwordx4 v[216:217], v[42:45], off nt
	s_nop 1
	v_lshlrev_b32_e32 v42, 16, v146
	v_add_f32_e32 v38, v38, v42
	v_and_b32_e32 v42, 0xffff0000, v146
	v_add_f32_e32 v39, v39, v42
	v_lshlrev_b32_e32 v42, 16, v147
	v_fmac_f32_e32 v53, v38, v38
	v_add_f32_e32 v40, v40, v42
	v_and_b32_e32 v42, 0xffff0000, v147
	v_fmac_f32_e32 v53, v39, v39
	v_add_f32_e32 v41, v41, v42
	v_lshlrev_b32_e32 v42, 16, v148
	v_fmac_f32_e32 v53, v40, v40
	v_add_f32_e32 v42, v34, v42
	v_and_b32_e32 v34, 0xffff0000, v148
	v_fmac_f32_e32 v53, v41, v41
	v_add_f32_e32 v43, v35, v34
	v_lshlrev_b32_e32 v34, 16, v149
	v_fmac_f32_e32 v53, v42, v42
	v_add_f32_e32 v44, v36, v34
	v_and_b32_e32 v34, 0xffff0000, v149
	v_fmac_f32_e32 v53, v43, v43
	v_add_f32_e32 v37, v37, v34
	v_fmac_f32_e32 v53, v44, v44
	v_fmac_f32_e32 v53, v37, v37
	v_cvt_pk_bf16_f32 v34, v38, v39
	v_cvt_pk_bf16_f32 v35, v40, v41
	v_cvt_pk_bf16_f32 v36, v42, v43
	v_cvt_pk_bf16_f32 v37, v44, v37
	global_store_dwordx4 v[216:217], v[34:37], off offset:64 nt
	s_nop 1
	v_mov_b32_e32 v34, v53
	s_nop 1
	v_permlane16_swap_b32_e32 v53, v34
	v_add_f32_e32 v34, v53, v34
	v_mov_b32_e32 v35, v34
	s_nop 1
	v_permlane32_swap_b32_e32 v34, v35
	s_and_saveexec_b64 s[16:17], s[4:5]
	s_cbranch_execz .LBB0_1034
	s_add_u32 s18, s38, s14
	s_addc_u32 s19, s39, s15
	v_lshl_add_u64 v[36:37], v[210:211], 2, s[18:19]
	v_add_f32_e32 v34, v34, v35
	global_store_dword v[36:37], v34, off offset:576
.LBB0_1034:
	s_or_b64 exec, exec, s[16:17]
	v_lshlrev_b32_e32 v34, 16, v142
	v_add_f32_e32 v30, v30, v34
	v_and_b32_e32 v34, 0xffff0000, v142
	v_add_f32_e32 v31, v31, v34
	v_lshlrev_b32_e32 v34, 16, v143
	v_mul_f32_e32 v37, v31, v31
	v_add_f32_e32 v32, v32, v34
	v_and_b32_e32 v34, 0xffff0000, v143
	v_fmac_f32_e32 v37, v30, v30
	v_add_f32_e32 v33, v33, v34
	v_lshlrev_b32_e32 v34, 16, v144
	v_fmac_f32_e32 v37, v32, v32
	v_add_f32_e32 v34, v26, v34
	v_and_b32_e32 v26, 0xffff0000, v144
	v_fmac_f32_e32 v37, v33, v33
	v_add_f32_e32 v35, v27, v26
	v_lshlrev_b32_e32 v26, 16, v145
	v_fmac_f32_e32 v37, v34, v34
	v_add_f32_e32 v36, v28, v26
	v_and_b32_e32 v26, 0xffff0000, v145
	v_fmac_f32_e32 v37, v35, v35
	v_add_f32_e32 v29, v29, v26
	v_fmac_f32_e32 v37, v36, v36
	v_cvt_pk_bf16_f32 v26, v30, v31
	v_fmac_f32_e32 v37, v29, v29
	v_cvt_pk_bf16_f32 v27, v32, v33
	v_cvt_pk_bf16_f32 v28, v34, v35
	v_cvt_pk_bf16_f32 v29, v36, v29
	global_store_dwordx4 v[214:215], v[26:29], off nt
	s_nop 1
	v_lshlrev_b32_e32 v26, 16, v134
	v_add_f32_e32 v22, v22, v26
	v_and_b32_e32 v26, 0xffff0000, v134
	v_add_f32_e32 v23, v23, v26
	v_lshlrev_b32_e32 v26, 16, v135
	v_fmac_f32_e32 v37, v22, v22
	v_add_f32_e32 v24, v24, v26
	v_and_b32_e32 v26, 0xffff0000, v135
	v_fmac_f32_e32 v37, v23, v23
	v_add_f32_e32 v25, v25, v26
	v_lshlrev_b32_e32 v26, 16, v136
	v_fmac_f32_e32 v37, v24, v24
	v_add_f32_e32 v26, v18, v26
	v_and_b32_e32 v18, 0xffff0000, v136
	v_fmac_f32_e32 v37, v25, v25
	v_add_f32_e32 v27, v19, v18
	v_lshlrev_b32_e32 v18, 16, v137
	v_fmac_f32_e32 v37, v26, v26
	v_add_f32_e32 v28, v20, v18
	v_and_b32_e32 v18, 0xffff0000, v137
	v_fmac_f32_e32 v37, v27, v27
	v_add_f32_e32 v21, v21, v18
	v_fmac_f32_e32 v37, v28, v28
	v_fmac_f32_e32 v37, v21, v21
	v_cvt_pk_bf16_f32 v18, v22, v23
	v_cvt_pk_bf16_f32 v19, v24, v25
	v_cvt_pk_bf16_f32 v20, v26, v27
	v_cvt_pk_bf16_f32 v21, v28, v21
	global_store_dwordx4 v[214:215], v[18:21], off offset:64 nt
	s_nop 1
	v_mov_b32_e32 v18, v37
	s_nop 1
	v_permlane16_swap_b32_e32 v37, v18
	v_add_f32_e32 v18, v37, v18
	v_mov_b32_e32 v19, v18
	s_nop 1
	v_permlane32_swap_b32_e32 v18, v19
	s_and_saveexec_b64 s[16:17], s[4:5]
	s_cbranch_execz .LBB0_1036
	s_add_u32 s18, s38, s14
	s_addc_u32 s19, s39, s15
	v_lshl_add_u64 v[20:21], v[210:211], 2, s[18:19]
	v_add_f32_e32 v18, v18, v19
	global_store_dword v[20:21], v18, off offset:640
.LBB0_1036:
	s_or_b64 exec, exec, s[16:17]
	v_lshlrev_b32_e32 v18, 16, v138
	v_add_f32_e32 v14, v14, v18
	v_and_b32_e32 v18, 0xffff0000, v138
	v_add_f32_e32 v15, v15, v18
	v_lshlrev_b32_e32 v18, 16, v139
	v_mul_f32_e32 v21, v15, v15
	v_add_f32_e32 v16, v16, v18
	v_and_b32_e32 v18, 0xffff0000, v139
	v_fmac_f32_e32 v21, v14, v14
	v_add_f32_e32 v17, v17, v18
	v_lshlrev_b32_e32 v18, 16, v140
	v_fmac_f32_e32 v21, v16, v16
	v_add_f32_e32 v18, v10, v18
	v_and_b32_e32 v10, 0xffff0000, v140
	v_fmac_f32_e32 v21, v17, v17
	v_add_f32_e32 v19, v11, v10
	v_lshlrev_b32_e32 v10, 16, v141
	v_fmac_f32_e32 v21, v18, v18
	v_add_f32_e32 v20, v12, v10
	v_and_b32_e32 v10, 0xffff0000, v141
	v_fmac_f32_e32 v21, v19, v19
	v_add_f32_e32 v13, v13, v10
	v_fmac_f32_e32 v21, v20, v20
	v_cvt_pk_bf16_f32 v10, v14, v15
	v_fmac_f32_e32 v21, v13, v13
	v_cvt_pk_bf16_f32 v11, v16, v17
	v_cvt_pk_bf16_f32 v12, v18, v19
	v_cvt_pk_bf16_f32 v13, v20, v13
	global_store_dwordx4 v[212:213], v[10:13], off nt
	s_nop 1
	v_lshlrev_b32_e32 v10, 16, v130
	v_add_f32_e32 v6, v6, v10
	v_and_b32_e32 v10, 0xffff0000, v130
	v_add_f32_e32 v7, v7, v10
	v_lshlrev_b32_e32 v10, 16, v131
	v_fmac_f32_e32 v21, v6, v6
	v_add_f32_e32 v8, v8, v10
	v_and_b32_e32 v10, 0xffff0000, v131
	v_fmac_f32_e32 v21, v7, v7
	v_add_f32_e32 v9, v9, v10
	v_lshlrev_b32_e32 v10, 16, v132
	v_fmac_f32_e32 v21, v8, v8
	v_add_f32_e32 v10, v2, v10
	v_and_b32_e32 v2, 0xffff0000, v132
	v_fmac_f32_e32 v21, v9, v9
	v_add_f32_e32 v11, v3, v2
	v_lshlrev_b32_e32 v2, 16, v133
	v_fmac_f32_e32 v21, v10, v10
	v_add_f32_e32 v12, v4, v2
	v_and_b32_e32 v2, 0xffff0000, v133
	v_fmac_f32_e32 v21, v11, v11
	v_add_f32_e32 v5, v5, v2
	v_fmac_f32_e32 v21, v12, v12
	v_fmac_f32_e32 v21, v5, v5
	v_cvt_pk_bf16_f32 v2, v6, v7
	v_cvt_pk_bf16_f32 v3, v8, v9
	v_cvt_pk_bf16_f32 v4, v10, v11
	v_cvt_pk_bf16_f32 v5, v12, v5
	global_store_dwordx4 v[212:213], v[2:5], off offset:64 nt
	s_nop 1
	v_mov_b32_e32 v2, v21
	s_nop 1
	v_permlane16_swap_b32_e32 v21, v2
	v_add_f32_e32 v2, v21, v2
	v_mov_b32_e32 v3, v2
	s_nop 1
	v_permlane32_swap_b32_e32 v2, v3
	s_and_saveexec_b64 s[16:17], s[4:5]
	s_cbranch_execz .LBB0_1013
	s_add_u32 s14, s38, s14
	s_addc_u32 s15, s39, s15
	v_lshl_add_u64 v[4:5], v[210:211], 2, s[14:15]
	v_add_f32_e32 v2, v2, v3
	global_store_dword v[4:5], v2, off offset:704
	s_branch .LBB0_1013
